# P4 mix-epilogue bf16 stores coalesced via ds_bpermute; P5 epilogue x loads and y stores both in permuted lane order with accumulators permuted in place
# speedup vs baseline: 1.0283x; 1.0074x over previous
;     DEVI void init() { G = gridDim.x; const int b = blockIdx.x; if ((G & 7) == 0) { x = b & 7; j = b >> 3; nloc = G >> 3; } else { x = -1; j = b; nloc = G; } }
;     DEVI void init(bool pr) { pair = pr; G = gridDim.x; const int b = blockIdx.x; if ((G & 7) == 0) { x = b & 7; j = b >> 3; nloc = G >> 3; } else { x = -1; j = b; nloc = G; } }
;     DEVI void operator()(const f32x4 (&acc)[2][2][4][2], const pg8::Unit& u, int wr, int wc, int l15, int g) const {
;         const bf16_t* G = (const bf16_t*)pp->out;
;         bf16_t* MX = (bf16_t*)(pp->ws + W_XN);
;         const int colb = u.pn * 256 + 32 * wc + 4 * g;
; template <int PH>
; DEVI void run_phase(const Params& p, unsigned char* smem) {
;     ...
;         EpiMix epi; epi.pp = &p;
;         const bf16_t* OA = (const bf16_t*)(p.ws + W_OAB); const bf16_t* WAT = (const bf16_t*)(p.ws + W_WABT);
;         pg8::Gemm g{OA, WAT, OA + (size_t)NTOK * 512, WAT + 1024 * 512, 512};
;         OrderP4 S; S.init(true);
;         pg8::gemm_phase(lds, g, S, epi);
.LBB0_999:
	v_and_b32_e32 v238, 63, v203
	v_and_b32_e32 v239, 3, v238
	v_lshrrev_b32_e32 v237, 4, v238
	v_bfe_u32 v236, v238, 2, 2
	v_lshl_add_u32 v237, v237, 2, v236
	v_and_b32_e32 v236, 1, v239
	v_lshrrev_b32_e32 v239, 1, v239
	v_lshl_or_b32 v239, v236, 1, v239
	v_lshl_add_u32 v239, v239, 4, v237
	v_lshlrev_b32_e32 v239, 2, v239
	v_mov_b32_e32 v8, v203
	s_and_b64 vcc, exec, s[78:79]
	v_readfirstlane_b32 s10, v8
	s_cbranch_vccz .LBB0_1163
	s_cmpk_lt_i32 s91, 0x200
	s_cselect_b64 s[0:1], -1, 0
	s_mov_b32 s2, s74
	s_cbranch_execnz .LBB0_1002

; DEVI unsigned pk_bf16(float lo, float hi) { const f32x2_t v = {lo, hi}; const bf16x2_t b = __builtin_convertvector(v, bf16x2_t); return __builtin_bit_cast(unsigned, b); }
; DEVI float bf_lo(unsigned u) { return __uint_as_float(u << 16); }
; DEVI float bf_hi(unsigned u) { return __uint_as_float(u & 0xffff0000u); }
;     DEVI void operator()(const f32x4 (&acc)[2][2][4][2], const pg8::Unit& u, int wr, int wc, int l15, int g) const {
;     ...
;                     unsigned pk[2][2];
; #pragma unroll
;                     for (int n = 0; n < 2; ++n) {
;                         const f32x4 a = acc[ai][bj][m][n];
;                         const u32x2 gg = gq[m][bj][n];
;                         f32x4 t;
;                         t[0] = a[0] * bf_lo(gg.x); t[1] = a[1] * bf_hi(gg.x); t[2] = a[2] * bf_lo(gg.y); t[3] = a[3] * bf_hi(gg.y);
;                         if (u.w) { const u32x2 q = pv[m][bj][n]; t[0] += bf_lo(q.x); t[1] += bf_hi(q.x); t[2] += bf_lo(q.y); t[3] += bf_hi(q.y); }
;                         pk[n][0] = pk_bf16(t[0], t[1]); pk[n][1] = pk_bf16(t[2], t[3]);
;                     }
;                     const auto r0 = __builtin_amdgcn_permlane16_swap(pk[0][0], pk[1][0], false, false);
;                     const auto r1 = __builtin_amdgcn_permlane16_swap(pk[0][1], pk[1][1], false, false);
;                     const u32x4 o = (u32x4){r0[0], r1[0], r0[1], r1[1]};
;                     *(u32x4*)(MX + (size_t)tok * 1024 + u.pn * 256 + 32 * wc + 128 * bj + 16 * (g & 1) + 8 * (g >> 1)) = o;
.LBB0_1039:
	v_lshl_add_u64 v[172:173], s[12:13], 0, v[172:173]
	s_ashr_i32 s25, s24, 31
	v_cvt_pk_bf16_f32 v124, v124, v125
	v_cvt_pk_bf16_f32 v125, v126, v127
	v_cvt_pk_bf16_f32 v126, v120, v121
	v_cvt_pk_bf16_f32 v127, v122, v123
	v_lshl_add_u64 v[120:121], s[24:25], 1, v[172:173]
	v_lshlrev_b32_e32 v122, 16, v170
	v_and_b32_e32 v123, 0xffff0000, v170
	v_lshl_add_u64 v[120:121], v[120:121], 0, v[132:133]
	v_mov_b32_e32 v139, v133
	v_pk_mul_f32 v[116:117], v[116:117], v[122:123]
	v_lshlrev_b32_e32 v122, 16, v171
	v_and_b32_e32 v123, 0xffff0000, v171
	v_permlane16_swap_b32_e32 v124, v126
	v_permlane16_swap_b32_e32 v125, v127
	v_lshl_add_u64 v[120:121], v[120:121], 0, v[138:139]
	s_and_b64 vcc, exec, s[4:5]
	v_pk_mul_f32 v[118:119], v[118:119], v[122:123]
	ds_bpermute_b32 v236, v239, v120
	ds_bpermute_b32 v237, v239, v121
	ds_bpermute_b32 v240, v239, v124
	ds_bpermute_b32 v241, v239, v125
	ds_bpermute_b32 v242, v239, v126
	ds_bpermute_b32 v243, v239, v127
	s_waitcnt lgkmcnt(0)
	global_store_dwordx4 v[236:237], v[240:243], off
	s_cbranch_vccnz .LBB0_1041
	v_lshlrev_b32_e32 v122, 16, v154
	v_and_b32_e32 v123, 0xffff0000, v154
	v_pk_add_f32 v[116:117], v[116:117], v[122:123]
	v_lshlrev_b32_e32 v122, 16, v155
	v_and_b32_e32 v123, 0xffff0000, v155
	v_pk_add_f32 v[118:119], v[118:119], v[122:123]

; DEVI unsigned pk_bf16(float lo, float hi) { const f32x2_t v = {lo, hi}; const bf16x2_t b = __builtin_convertvector(v, bf16x2_t); return __builtin_bit_cast(unsigned, b); }
; DEVI float bf_lo(unsigned u) { return __uint_as_float(u << 16); }
; DEVI float bf_hi(unsigned u) { return __uint_as_float(u & 0xffff0000u); }
;     DEVI void operator()(const f32x4 (&acc)[2][2][4][2], const pg8::Unit& u, int wr, int wc, int l15, int g) const {
;     ...
;                     unsigned pk[2][2];
; #pragma unroll
;                     for (int n = 0; n < 2; ++n) {
;                         const f32x4 a = acc[ai][bj][m][n];
;                         const u32x2 gg = gq[m][bj][n];
;                         f32x4 t;
;                         t[0] = a[0] * bf_lo(gg.x); t[1] = a[1] * bf_hi(gg.x); t[2] = a[2] * bf_lo(gg.y); t[3] = a[3] * bf_hi(gg.y);
;                         if (u.w) { const u32x2 q = pv[m][bj][n]; t[0] += bf_lo(q.x); t[1] += bf_hi(q.x); t[2] += bf_lo(q.y); t[3] += bf_hi(q.y); }
;                         pk[n][0] = pk_bf16(t[0], t[1]); pk[n][1] = pk_bf16(t[2], t[3]);
;                     }
;                     const auto r0 = __builtin_amdgcn_permlane16_swap(pk[0][0], pk[1][0], false, false);
;                     const auto r1 = __builtin_amdgcn_permlane16_swap(pk[0][1], pk[1][1], false, false);
;                     const u32x4 o = (u32x4){r0[0], r1[0], r0[1], r1[1]};
;                     *(u32x4*)(MX + (size_t)tok * 1024 + u.pn * 256 + 32 * wc + 128 * bj + 16 * (g & 1) + 8 * (g >> 1)) = o;
.LBB0_1043:
	v_cvt_pk_bf16_f32 v116, v116, v117
	v_cvt_pk_bf16_f32 v117, v118, v119
	v_cvt_pk_bf16_f32 v118, v112, v113
	v_lshlrev_b32_e32 v112, 16, v166
	v_and_b32_e32 v113, 0xffff0000, v166
	v_cvt_pk_bf16_f32 v119, v114, v115
	v_pk_mul_f32 v[108:109], v[108:109], v[112:113]
	v_lshlrev_b32_e32 v112, 16, v167
	v_and_b32_e32 v113, 0xffff0000, v167
	v_permlane16_swap_b32_e32 v116, v118
	v_permlane16_swap_b32_e32 v117, v119
	s_and_b64 vcc, exec, s[4:5]
	v_pk_mul_f32 v[110:111], v[110:111], v[112:113]
	ds_bpermute_b32 v236, v239, v120
	ds_bpermute_b32 v237, v239, v121
	ds_bpermute_b32 v244, v239, v116
	ds_bpermute_b32 v245, v239, v117
	ds_bpermute_b32 v246, v239, v118
	ds_bpermute_b32 v247, v239, v119
	s_waitcnt lgkmcnt(0)
	global_store_dwordx4 v[236:237], v[244:247], off offset:256
	s_cbranch_vccnz .LBB0_1045
	v_lshlrev_b32_e32 v112, 16, v150
	v_and_b32_e32 v113, 0xffff0000, v150
	v_pk_add_f32 v[108:109], v[108:109], v[112:113]
	v_lshlrev_b32_e32 v112, 16, v151
	v_and_b32_e32 v113, 0xffff0000, v151
	v_pk_add_f32 v[110:111], v[110:111], v[112:113]

; DEVI unsigned pk_bf16(float lo, float hi) { const f32x2_t v = {lo, hi}; const bf16x2_t b = __builtin_convertvector(v, bf16x2_t); return __builtin_bit_cast(unsigned, b); }
; DEVI float bf_lo(unsigned u) { return __uint_as_float(u << 16); }
; DEVI float bf_hi(unsigned u) { return __uint_as_float(u & 0xffff0000u); }
;     DEVI void operator()(const f32x4 (&acc)[2][2][4][2], const pg8::Unit& u, int wr, int wc, int l15, int g) const {
;     ...
;                     unsigned pk[2][2];
; #pragma unroll
;                     for (int n = 0; n < 2; ++n) {
;                         const f32x4 a = acc[ai][bj][m][n];
;                         const u32x2 gg = gq[m][bj][n];
;                         f32x4 t;
;                         t[0] = a[0] * bf_lo(gg.x); t[1] = a[1] * bf_hi(gg.x); t[2] = a[2] * bf_lo(gg.y); t[3] = a[3] * bf_hi(gg.y);
;                         if (u.w) { const u32x2 q = pv[m][bj][n]; t[0] += bf_lo(q.x); t[1] += bf_hi(q.x); t[2] += bf_lo(q.y); t[3] += bf_hi(q.y); }
;                         pk[n][0] = pk_bf16(t[0], t[1]); pk[n][1] = pk_bf16(t[2], t[3]);
;                     }
;                     const auto r0 = __builtin_amdgcn_permlane16_swap(pk[0][0], pk[1][0], false, false);
;                     const auto r1 = __builtin_amdgcn_permlane16_swap(pk[0][1], pk[1][1], false, false);
;                     const u32x4 o = (u32x4){r0[0], r1[0], r0[1], r1[1]};
;                     *(u32x4*)(MX + (size_t)tok * 1024 + u.pn * 256 + 32 * wc + 128 * bj + 16 * (g & 1) + 8 * (g >> 1)) = o;
.LBB0_1047:
	v_cvt_pk_bf16_f32 v108, v108, v109
	v_cvt_pk_bf16_f32 v109, v110, v111
	v_add_u32_e32 v110, s15, v183
	v_ashrrev_i32_e32 v111, 31, v110
	v_lshlrev_b64 v[110:111], 11, v[110:111]
	v_lshl_add_u64 v[112:113], s[12:13], 0, v[110:111]
	v_cvt_pk_bf16_f32 v110, v104, v105
	v_cvt_pk_bf16_f32 v111, v106, v107
	v_lshl_add_u64 v[104:105], s[24:25], 1, v[112:113]
	v_lshlrev_b32_e32 v106, 16, v162
	v_and_b32_e32 v107, 0xffff0000, v162
	v_lshl_add_u64 v[104:105], v[104:105], 0, v[132:133]
	v_mov_b32_e32 v139, v133
	v_pk_mul_f32 v[100:101], v[100:101], v[106:107]
	v_lshlrev_b32_e32 v106, 16, v163
	v_and_b32_e32 v107, 0xffff0000, v163
	v_permlane16_swap_b32_e32 v108, v110
	v_permlane16_swap_b32_e32 v109, v111
	v_lshl_add_u64 v[104:105], v[104:105], 0, v[138:139]
	s_and_b64 vcc, exec, s[4:5]
	v_pk_mul_f32 v[102:103], v[102:103], v[106:107]
	ds_bpermute_b32 v236, v239, v104
	ds_bpermute_b32 v237, v239, v105
	ds_bpermute_b32 v240, v239, v108
	ds_bpermute_b32 v241, v239, v109
	ds_bpermute_b32 v242, v239, v110
	ds_bpermute_b32 v243, v239, v111
	s_waitcnt lgkmcnt(0)
	global_store_dwordx4 v[236:237], v[240:243], off
	s_cbranch_vccnz .LBB0_1049
	v_lshlrev_b32_e32 v106, 16, v146
	v_and_b32_e32 v107, 0xffff0000, v146
	v_pk_add_f32 v[100:101], v[100:101], v[106:107]
	v_lshlrev_b32_e32 v106, 16, v147
	v_and_b32_e32 v107, 0xffff0000, v147
	v_pk_add_f32 v[102:103], v[102:103], v[106:107]

; DEVI unsigned pk_bf16(float lo, float hi) { const f32x2_t v = {lo, hi}; const bf16x2_t b = __builtin_convertvector(v, bf16x2_t); return __builtin_bit_cast(unsigned, b); }
; DEVI float bf_lo(unsigned u) { return __uint_as_float(u << 16); }
; DEVI float bf_hi(unsigned u) { return __uint_as_float(u & 0xffff0000u); }
;     DEVI void operator()(const f32x4 (&acc)[2][2][4][2], const pg8::Unit& u, int wr, int wc, int l15, int g) const {
;     ...
;             for (int m = 2 * mh; m < 2 * mh + 2; ++m) {
;                 const int tok = u.pm * 256 + 128 * ai + 64 * wr + 16 * m + l15;
; #pragma unroll
;                 for (int bj = 0; bj < 2; ++bj)
; #pragma unroll
;                     for (int n = 0; n < 2; ++n) {
;                         const int col = colb + 128 * bj + 16 * n;
;                         gq[m][bj][n] = *(const u32x2*)(G + (size_t)tok * 2048 + (u.w ? 1024 : 0) + col);
;                         if (u.w) pv[m][bj][n] = *(const u32x2*)(MX + (size_t)tok * 1024 + col);
;                     }
;     ...
;                     unsigned pk[2][2];
; #pragma unroll
;                     for (int n = 0; n < 2; ++n) {
;                         const f32x4 a = acc[ai][bj][m][n];
;                         const u32x2 gg = gq[m][bj][n];
;                         f32x4 t;
;                         t[0] = a[0] * bf_lo(gg.x); t[1] = a[1] * bf_hi(gg.x); t[2] = a[2] * bf_lo(gg.y); t[3] = a[3] * bf_hi(gg.y);
;                         if (u.w) { const u32x2 q = pv[m][bj][n]; t[0] += bf_lo(q.x); t[1] += bf_hi(q.x); t[2] += bf_lo(q.y); t[3] += bf_hi(q.y); }
;                         pk[n][0] = pk_bf16(t[0], t[1]); pk[n][1] = pk_bf16(t[2], t[3]);
;                     }
;                     const auto r0 = __builtin_amdgcn_permlane16_swap(pk[0][0], pk[1][0], false, false);
;                     const auto r1 = __builtin_amdgcn_permlane16_swap(pk[0][1], pk[1][1], false, false);
;                     const u32x4 o = (u32x4){r0[0], r1[0], r0[1], r1[1]};
;                     *(u32x4*)(MX + (size_t)tok * 1024 + u.pn * 256 + 32 * wc + 128 * bj + 16 * (g & 1) + 8 * (g >> 1)) = o;
.LBB0_1051:
	v_cvt_pk_bf16_f32 v100, v100, v101
	v_cvt_pk_bf16_f32 v101, v102, v103
	v_cvt_pk_bf16_f32 v102, v96, v97
	v_or_b32_e32 v96, 32, v140
	v_ashrrev_i32_e32 v97, 31, v96
	v_cvt_pk_bf16_f32 v103, v98, v99
	v_lshlrev_b64 v[98:99], 12, v[96:97]
	v_permlane16_swap_b32_e32 v100, v102
	v_permlane16_swap_b32_e32 v101, v103
	v_lshl_add_u64 v[98:99], s[26:27], 0, v[98:99]
	ds_bpermute_b32 v236, v239, v104
	ds_bpermute_b32 v237, v239, v105
	ds_bpermute_b32 v244, v239, v100
	ds_bpermute_b32 v245, v239, v101
	ds_bpermute_b32 v246, v239, v102
	ds_bpermute_b32 v247, v239, v103
	s_waitcnt lgkmcnt(0)
	global_store_dwordx4 v[236:237], v[244:247], off offset:256
	v_lshl_add_u64 v[98:99], v[142:143], 1, v[98:99]
	global_load_dwordx2 v[126:127], v[98:99], off
	v_lshlrev_b64 v[96:97], 11, v[96:97]
	v_lshl_add_u64 v[96:97], s[88:89], 0, v[96:97]
	s_and_b64 vcc, exec, s[4:5]
	v_lshl_add_u64 v[96:97], v[142:143], 1, v[96:97]
	s_cbranch_vccnz .LBB0_1055
	global_load_dwordx2 v[110:111], v[96:97], off
	global_load_dwordx2 v[124:125], v[98:99], off offset:32
	s_and_b64 vcc, exec, s[4:5]
	s_cbranch_vccz .LBB0_1056

; DEVI unsigned pk_bf16(float lo, float hi) { const f32x2_t v = {lo, hi}; const bf16x2_t b = __builtin_convertvector(v, bf16x2_t); return __builtin_bit_cast(unsigned, b); }
; DEVI float bf_lo(unsigned u) { return __uint_as_float(u << 16); }
; DEVI float bf_hi(unsigned u) { return __uint_as_float(u & 0xffff0000u); }
;     DEVI void operator()(const f32x4 (&acc)[2][2][4][2], const pg8::Unit& u, int wr, int wc, int l15, int g) const {
;     ...
;                     unsigned pk[2][2];
; #pragma unroll
;                     for (int n = 0; n < 2; ++n) {
;                         const f32x4 a = acc[ai][bj][m][n];
;                         const u32x2 gg = gq[m][bj][n];
;                         f32x4 t;
;                         t[0] = a[0] * bf_lo(gg.x); t[1] = a[1] * bf_hi(gg.x); t[2] = a[2] * bf_lo(gg.y); t[3] = a[3] * bf_hi(gg.y);
;                         if (u.w) { const u32x2 q = pv[m][bj][n]; t[0] += bf_lo(q.x); t[1] += bf_hi(q.x); t[2] += bf_lo(q.y); t[3] += bf_hi(q.y); }
;                         pk[n][0] = pk_bf16(t[0], t[1]); pk[n][1] = pk_bf16(t[2], t[3]);
;                     }
;                     const auto r0 = __builtin_amdgcn_permlane16_swap(pk[0][0], pk[1][0], false, false);
;                     const auto r1 = __builtin_amdgcn_permlane16_swap(pk[0][1], pk[1][1], false, false);
;                     const u32x4 o = (u32x4){r0[0], r1[0], r0[1], r1[1]};
;                     *(u32x4*)(MX + (size_t)tok * 1024 + u.pn * 256 + 32 * wc + 128 * bj + 16 * (g & 1) + 8 * (g >> 1)) = o;
.LBB0_1071:
	v_cvt_pk_bf16_f32 v92, v92, v93
	v_cvt_pk_bf16_f32 v93, v94, v95
	v_add_u32_e32 v94, s15, v184
	v_ashrrev_i32_e32 v95, 31, v94
	v_lshlrev_b64 v[94:95], 11, v[94:95]
	v_lshl_add_u64 v[124:125], s[12:13], 0, v[94:95]
	v_cvt_pk_bf16_f32 v94, v88, v89
	v_cvt_pk_bf16_f32 v95, v90, v91
	v_lshl_add_u64 v[88:89], s[24:25], 1, v[124:125]
	s_waitcnt vmcnt(5)
	v_lshlrev_b32_e32 v90, 16, v122
	v_and_b32_e32 v91, 0xffff0000, v122
	v_lshl_add_u64 v[88:89], v[88:89], 0, v[132:133]
	v_mov_b32_e32 v139, v133
	v_pk_mul_f32 v[84:85], v[84:85], v[90:91]
	v_lshlrev_b32_e32 v90, 16, v123
	v_and_b32_e32 v91, 0xffff0000, v123
	v_permlane16_swap_b32_e32 v92, v94
	v_permlane16_swap_b32_e32 v93, v95
	v_lshl_add_u64 v[88:89], v[88:89], 0, v[138:139]
	s_and_b64 vcc, exec, s[4:5]
	v_pk_mul_f32 v[86:87], v[86:87], v[90:91]
	ds_bpermute_b32 v236, v239, v88
	ds_bpermute_b32 v237, v239, v89
	ds_bpermute_b32 v240, v239, v92
	ds_bpermute_b32 v241, v239, v93
	ds_bpermute_b32 v242, v239, v94
	ds_bpermute_b32 v243, v239, v95
	s_waitcnt lgkmcnt(0)
	global_store_dwordx4 v[236:237], v[240:243], off
	s_cbranch_vccnz .LBB0_1073
	v_lshlrev_b32_e32 v90, 16, v106
	v_and_b32_e32 v91, 0xffff0000, v106
	v_pk_add_f32 v[84:85], v[84:85], v[90:91]
	v_lshlrev_b32_e32 v90, 16, v107
	v_and_b32_e32 v91, 0xffff0000, v107
	v_pk_add_f32 v[86:87], v[86:87], v[90:91]

; DEVI unsigned pk_bf16(float lo, float hi) { const f32x2_t v = {lo, hi}; const bf16x2_t b = __builtin_convertvector(v, bf16x2_t); return __builtin_bit_cast(unsigned, b); }
; DEVI float bf_lo(unsigned u) { return __uint_as_float(u << 16); }
; DEVI float bf_hi(unsigned u) { return __uint_as_float(u & 0xffff0000u); }
;     DEVI void operator()(const f32x4 (&acc)[2][2][4][2], const pg8::Unit& u, int wr, int wc, int l15, int g) const {
;     ...
;                     unsigned pk[2][2];
; #pragma unroll
;                     for (int n = 0; n < 2; ++n) {
;                         const f32x4 a = acc[ai][bj][m][n];
;                         const u32x2 gg = gq[m][bj][n];
;                         f32x4 t;
;                         t[0] = a[0] * bf_lo(gg.x); t[1] = a[1] * bf_hi(gg.x); t[2] = a[2] * bf_lo(gg.y); t[3] = a[3] * bf_hi(gg.y);
;                         if (u.w) { const u32x2 q = pv[m][bj][n]; t[0] += bf_lo(q.x); t[1] += bf_hi(q.x); t[2] += bf_lo(q.y); t[3] += bf_hi(q.y); }
;                         pk[n][0] = pk_bf16(t[0], t[1]); pk[n][1] = pk_bf16(t[2], t[3]);
;                     }
;                     const auto r0 = __builtin_amdgcn_permlane16_swap(pk[0][0], pk[1][0], false, false);
;                     const auto r1 = __builtin_amdgcn_permlane16_swap(pk[0][1], pk[1][1], false, false);
;                     const u32x4 o = (u32x4){r0[0], r1[0], r0[1], r1[1]};
;                     *(u32x4*)(MX + (size_t)tok * 1024 + u.pn * 256 + 32 * wc + 128 * bj + 16 * (g & 1) + 8 * (g >> 1)) = o;
.LBB0_1075:
	v_cvt_pk_bf16_f32 v84, v84, v85
	v_cvt_pk_bf16_f32 v85, v86, v87
	v_cvt_pk_bf16_f32 v86, v80, v81
	s_waitcnt vmcnt(4)
	v_lshlrev_b32_e32 v80, 16, v118
	v_and_b32_e32 v81, 0xffff0000, v118
	v_cvt_pk_bf16_f32 v87, v82, v83
	v_pk_mul_f32 v[76:77], v[76:77], v[80:81]
	v_lshlrev_b32_e32 v80, 16, v119
	v_and_b32_e32 v81, 0xffff0000, v119
	v_permlane16_swap_b32_e32 v84, v86
	v_permlane16_swap_b32_e32 v85, v87
	s_and_b64 vcc, exec, s[4:5]
	v_pk_mul_f32 v[78:79], v[78:79], v[80:81]
	ds_bpermute_b32 v236, v239, v88
	ds_bpermute_b32 v237, v239, v89
	ds_bpermute_b32 v244, v239, v84
	ds_bpermute_b32 v245, v239, v85
	ds_bpermute_b32 v246, v239, v86
	ds_bpermute_b32 v247, v239, v87
	s_waitcnt lgkmcnt(0)
	global_store_dwordx4 v[236:237], v[244:247], off offset:256
	s_cbranch_vccnz .LBB0_1077
	v_lshlrev_b32_e32 v80, 16, v102
	v_and_b32_e32 v81, 0xffff0000, v102
	v_pk_add_f32 v[76:77], v[76:77], v[80:81]
	v_lshlrev_b32_e32 v80, 16, v103
	v_and_b32_e32 v81, 0xffff0000, v103
	v_pk_add_f32 v[78:79], v[78:79], v[80:81]

; DEVI unsigned pk_bf16(float lo, float hi) { const f32x2_t v = {lo, hi}; const bf16x2_t b = __builtin_convertvector(v, bf16x2_t); return __builtin_bit_cast(unsigned, b); }
; DEVI float bf_lo(unsigned u) { return __uint_as_float(u << 16); }
; DEVI float bf_hi(unsigned u) { return __uint_as_float(u & 0xffff0000u); }
;     DEVI void operator()(const f32x4 (&acc)[2][2][4][2], const pg8::Unit& u, int wr, int wc, int l15, int g) const {
;     ...
;                     unsigned pk[2][2];
; #pragma unroll
;                     for (int n = 0; n < 2; ++n) {
;                         const f32x4 a = acc[ai][bj][m][n];
;                         const u32x2 gg = gq[m][bj][n];
;                         f32x4 t;
;                         t[0] = a[0] * bf_lo(gg.x); t[1] = a[1] * bf_hi(gg.x); t[2] = a[2] * bf_lo(gg.y); t[3] = a[3] * bf_hi(gg.y);
;                         if (u.w) { const u32x2 q = pv[m][bj][n]; t[0] += bf_lo(q.x); t[1] += bf_hi(q.x); t[2] += bf_lo(q.y); t[3] += bf_hi(q.y); }
;                         pk[n][0] = pk_bf16(t[0], t[1]); pk[n][1] = pk_bf16(t[2], t[3]);
;                     }
;                     const auto r0 = __builtin_amdgcn_permlane16_swap(pk[0][0], pk[1][0], false, false);
;                     const auto r1 = __builtin_amdgcn_permlane16_swap(pk[0][1], pk[1][1], false, false);
;                     const u32x4 o = (u32x4){r0[0], r1[0], r0[1], r1[1]};
;                     *(u32x4*)(MX + (size_t)tok * 1024 + u.pn * 256 + 32 * wc + 128 * bj + 16 * (g & 1) + 8 * (g >> 1)) = o;
.LBB0_1079:
	v_cvt_pk_bf16_f32 v76, v76, v77
	v_cvt_pk_bf16_f32 v77, v78, v79
	v_add_u32_e32 v78, s15, v185
	v_ashrrev_i32_e32 v79, 31, v78
	v_lshlrev_b64 v[78:79], 11, v[78:79]
	v_lshl_add_u64 v[80:81], s[12:13], 0, v[78:79]
	v_cvt_pk_bf16_f32 v78, v72, v73
	v_cvt_pk_bf16_f32 v79, v74, v75
	v_lshl_add_u64 v[72:73], s[24:25], 1, v[80:81]
	s_waitcnt vmcnt(3)
	v_lshlrev_b32_e32 v74, 16, v114
	v_and_b32_e32 v75, 0xffff0000, v114
	v_lshl_add_u64 v[72:73], v[72:73], 0, v[132:133]
	v_mov_b32_e32 v139, v133
	v_pk_mul_f32 v[68:69], v[68:69], v[74:75]
	v_lshlrev_b32_e32 v74, 16, v115
	v_and_b32_e32 v75, 0xffff0000, v115
	v_permlane16_swap_b32_e32 v76, v78
	v_permlane16_swap_b32_e32 v77, v79
	v_lshl_add_u64 v[72:73], v[72:73], 0, v[138:139]
	s_and_b64 vcc, exec, s[4:5]
	v_pk_mul_f32 v[70:71], v[70:71], v[74:75]
	ds_bpermute_b32 v236, v239, v72
	ds_bpermute_b32 v237, v239, v73
	ds_bpermute_b32 v240, v239, v76
	ds_bpermute_b32 v241, v239, v77
	ds_bpermute_b32 v242, v239, v78
	ds_bpermute_b32 v243, v239, v79
	s_waitcnt lgkmcnt(0)
	global_store_dwordx4 v[236:237], v[240:243], off
	s_cbranch_vccnz .LBB0_1081
	v_lshlrev_b32_e32 v74, 16, v98
	v_and_b32_e32 v75, 0xffff0000, v98
	v_pk_add_f32 v[68:69], v[68:69], v[74:75]
	v_lshlrev_b32_e32 v74, 16, v99
	v_and_b32_e32 v75, 0xffff0000, v99
	v_pk_add_f32 v[70:71], v[70:71], v[74:75]

; DEVI unsigned pk_bf16(float lo, float hi) { const f32x2_t v = {lo, hi}; const bf16x2_t b = __builtin_convertvector(v, bf16x2_t); return __builtin_bit_cast(unsigned, b); }
; DEVI float bf_lo(unsigned u) { return __uint_as_float(u << 16); }
; DEVI float bf_hi(unsigned u) { return __uint_as_float(u & 0xffff0000u); }
;     DEVI void operator()(const f32x4 (&acc)[2][2][4][2], const pg8::Unit& u, int wr, int wc, int l15, int g) const {
;     ...
;             for (int m = 2 * mh; m < 2 * mh + 2; ++m) {
;                 const int tok = u.pm * 256 + 128 * ai + 64 * wr + 16 * m + l15;
; #pragma unroll
;                 for (int bj = 0; bj < 2; ++bj)
; #pragma unroll
;                     for (int n = 0; n < 2; ++n) {
;                         const int col = colb + 128 * bj + 16 * n;
;                         gq[m][bj][n] = *(const u32x2*)(G + (size_t)tok * 2048 + (u.w ? 1024 : 0) + col);
;                         if (u.w) pv[m][bj][n] = *(const u32x2*)(MX + (size_t)tok * 1024 + col);
;                     }
;     ...
;                     unsigned pk[2][2];
; #pragma unroll
;                     for (int n = 0; n < 2; ++n) {
;                         const f32x4 a = acc[ai][bj][m][n];
;                         const u32x2 gg = gq[m][bj][n];
;                         f32x4 t;
;                         t[0] = a[0] * bf_lo(gg.x); t[1] = a[1] * bf_hi(gg.x); t[2] = a[2] * bf_lo(gg.y); t[3] = a[3] * bf_hi(gg.y);
;                         if (u.w) { const u32x2 q = pv[m][bj][n]; t[0] += bf_lo(q.x); t[1] += bf_hi(q.x); t[2] += bf_lo(q.y); t[3] += bf_hi(q.y); }
;                         pk[n][0] = pk_bf16(t[0], t[1]); pk[n][1] = pk_bf16(t[2], t[3]);
;                     }
;                     const auto r0 = __builtin_amdgcn_permlane16_swap(pk[0][0], pk[1][0], false, false);
;                     const auto r1 = __builtin_amdgcn_permlane16_swap(pk[0][1], pk[1][1], false, false);
;                     const u32x4 o = (u32x4){r0[0], r1[0], r0[1], r1[1]};
;                     *(u32x4*)(MX + (size_t)tok * 1024 + u.pn * 256 + 32 * wc + 128 * bj + 16 * (g & 1) + 8 * (g >> 1)) = o;
.LBB0_1083:
	v_cvt_pk_bf16_f32 v68, v68, v69
	v_cvt_pk_bf16_f32 v69, v70, v71
	v_cvt_pk_bf16_f32 v70, v64, v65
	v_add_u32_e32 v64, 0x80, v140
	v_ashrrev_i32_e32 v65, 31, v64
	v_cvt_pk_bf16_f32 v71, v66, v67
	v_lshlrev_b64 v[66:67], 12, v[64:65]
	v_permlane16_swap_b32_e32 v68, v70
	v_permlane16_swap_b32_e32 v69, v71
	v_lshl_add_u64 v[66:67], s[26:27], 0, v[66:67]
	ds_bpermute_b32 v236, v239, v72
	ds_bpermute_b32 v237, v239, v73
	ds_bpermute_b32 v244, v239, v68
	ds_bpermute_b32 v245, v239, v69
	ds_bpermute_b32 v246, v239, v70
	ds_bpermute_b32 v247, v239, v71
	s_waitcnt lgkmcnt(0)
	global_store_dwordx4 v[236:237], v[244:247], off offset:256
	v_lshlrev_b64 v[78:79], 11, v[64:65]
	s_and_b64 vcc, exec, s[4:5]
	v_lshl_add_u64 v[68:69], v[142:143], 1, v[66:67]
	global_load_dwordx2 v[82:83], v[68:69], off
	v_lshl_add_u64 v[66:67], s[88:89], 0, v[78:79]
	v_lshl_add_u64 v[66:67], v[142:143], 1, v[66:67]
	s_cbranch_vccnz .LBB0_1087
	global_load_dwordx2 v[158:159], v[66:67], off
	global_load_dwordx2 v[80:81], v[68:69], off offset:32
	s_and_b64 vcc, exec, s[4:5]
	s_cbranch_vccz .LBB0_1088

; DEVI unsigned pk_bf16(float lo, float hi) { const f32x2_t v = {lo, hi}; const bf16x2_t b = __builtin_convertvector(v, bf16x2_t); return __builtin_bit_cast(unsigned, b); }
; DEVI float bf_lo(unsigned u) { return __uint_as_float(u << 16); }
; DEVI float bf_hi(unsigned u) { return __uint_as_float(u & 0xffff0000u); }
;     DEVI void operator()(const f32x4 (&acc)[2][2][4][2], const pg8::Unit& u, int wr, int wc, int l15, int g) const {
;     ...
;                     unsigned pk[2][2];
; #pragma unroll
;                     for (int n = 0; n < 2; ++n) {
;                         const f32x4 a = acc[ai][bj][m][n];
;                         const u32x2 gg = gq[m][bj][n];
;                         f32x4 t;
;                         t[0] = a[0] * bf_lo(gg.x); t[1] = a[1] * bf_hi(gg.x); t[2] = a[2] * bf_lo(gg.y); t[3] = a[3] * bf_hi(gg.y);
;                         if (u.w) { const u32x2 q = pv[m][bj][n]; t[0] += bf_lo(q.x); t[1] += bf_hi(q.x); t[2] += bf_lo(q.y); t[3] += bf_hi(q.y); }
;                         pk[n][0] = pk_bf16(t[0], t[1]); pk[n][1] = pk_bf16(t[2], t[3]);
;                     }
;                     const auto r0 = __builtin_amdgcn_permlane16_swap(pk[0][0], pk[1][0], false, false);
;                     const auto r1 = __builtin_amdgcn_permlane16_swap(pk[0][1], pk[1][1], false, false);
;                     const u32x4 o = (u32x4){r0[0], r1[0], r0[1], r1[1]};
;                     *(u32x4*)(MX + (size_t)tok * 1024 + u.pn * 256 + 32 * wc + 128 * bj + 16 * (g & 1) + 8 * (g >> 1)) = o;
.LBB0_1103:
	v_lshl_add_u64 v[78:79], s[12:13], 0, v[78:79]
	v_cvt_pk_bf16_f32 v60, v60, v61
	v_cvt_pk_bf16_f32 v61, v62, v63
	v_cvt_pk_bf16_f32 v62, v56, v57
	v_cvt_pk_bf16_f32 v63, v58, v59
	v_lshl_add_u64 v[56:57], s[24:25], 1, v[78:79]
	s_waitcnt vmcnt(5)
	v_lshlrev_b32_e32 v58, 16, v76
	v_and_b32_e32 v59, 0xffff0000, v76
	v_lshl_add_u64 v[56:57], v[56:57], 0, v[132:133]
	v_mov_b32_e32 v139, v133
	v_pk_mul_f32 v[52:53], v[52:53], v[58:59]
	v_lshlrev_b32_e32 v58, 16, v77
	v_and_b32_e32 v59, 0xffff0000, v77
	v_permlane16_swap_b32_e32 v60, v62
	v_permlane16_swap_b32_e32 v61, v63
	v_lshl_add_u64 v[56:57], v[56:57], 0, v[138:139]
	s_and_b64 vcc, exec, s[4:5]
	v_pk_mul_f32 v[54:55], v[54:55], v[58:59]
	ds_bpermute_b32 v236, v239, v56
	ds_bpermute_b32 v237, v239, v57
	ds_bpermute_b32 v240, v239, v60
	ds_bpermute_b32 v241, v239, v61
	ds_bpermute_b32 v242, v239, v62
	ds_bpermute_b32 v243, v239, v63
	s_waitcnt lgkmcnt(0)
	global_store_dwordx4 v[236:237], v[240:243], off
	s_cbranch_vccnz .LBB0_1105
	v_lshlrev_b32_e32 v58, 16, v154
	v_and_b32_e32 v59, 0xffff0000, v154
	v_pk_add_f32 v[52:53], v[52:53], v[58:59]
	v_lshlrev_b32_e32 v58, 16, v155
	v_and_b32_e32 v59, 0xffff0000, v155
	v_pk_add_f32 v[54:55], v[54:55], v[58:59]

; DEVI unsigned pk_bf16(float lo, float hi) { const f32x2_t v = {lo, hi}; const bf16x2_t b = __builtin_convertvector(v, bf16x2_t); return __builtin_bit_cast(unsigned, b); }
; DEVI float bf_lo(unsigned u) { return __uint_as_float(u << 16); }
; DEVI float bf_hi(unsigned u) { return __uint_as_float(u & 0xffff0000u); }
;     DEVI void operator()(const f32x4 (&acc)[2][2][4][2], const pg8::Unit& u, int wr, int wc, int l15, int g) const {
;     ...
;                     unsigned pk[2][2];
; #pragma unroll
;                     for (int n = 0; n < 2; ++n) {
;                         const f32x4 a = acc[ai][bj][m][n];
;                         const u32x2 gg = gq[m][bj][n];
;                         f32x4 t;
;                         t[0] = a[0] * bf_lo(gg.x); t[1] = a[1] * bf_hi(gg.x); t[2] = a[2] * bf_lo(gg.y); t[3] = a[3] * bf_hi(gg.y);
;                         if (u.w) { const u32x2 q = pv[m][bj][n]; t[0] += bf_lo(q.x); t[1] += bf_hi(q.x); t[2] += bf_lo(q.y); t[3] += bf_hi(q.y); }
;                         pk[n][0] = pk_bf16(t[0], t[1]); pk[n][1] = pk_bf16(t[2], t[3]);
;                     }
;                     const auto r0 = __builtin_amdgcn_permlane16_swap(pk[0][0], pk[1][0], false, false);
;                     const auto r1 = __builtin_amdgcn_permlane16_swap(pk[0][1], pk[1][1], false, false);
;                     const u32x4 o = (u32x4){r0[0], r1[0], r0[1], r1[1]};
;                     *(u32x4*)(MX + (size_t)tok * 1024 + u.pn * 256 + 32 * wc + 128 * bj + 16 * (g & 1) + 8 * (g >> 1)) = o;
.LBB0_1107:
	v_cvt_pk_bf16_f32 v52, v52, v53
	v_cvt_pk_bf16_f32 v53, v54, v55
	v_cvt_pk_bf16_f32 v54, v48, v49
	s_waitcnt vmcnt(4)
	v_lshlrev_b32_e32 v48, 16, v72
	v_and_b32_e32 v49, 0xffff0000, v72
	v_cvt_pk_bf16_f32 v55, v50, v51
	v_pk_mul_f32 v[44:45], v[44:45], v[48:49]
	v_lshlrev_b32_e32 v48, 16, v73
	v_and_b32_e32 v49, 0xffff0000, v73
	v_permlane16_swap_b32_e32 v52, v54
	v_permlane16_swap_b32_e32 v53, v55
	s_and_b64 vcc, exec, s[4:5]
	v_pk_mul_f32 v[46:47], v[46:47], v[48:49]
	ds_bpermute_b32 v236, v239, v56
	ds_bpermute_b32 v237, v239, v57
	ds_bpermute_b32 v244, v239, v52
	ds_bpermute_b32 v245, v239, v53
	ds_bpermute_b32 v246, v239, v54
	ds_bpermute_b32 v247, v239, v55
	s_waitcnt lgkmcnt(0)
	global_store_dwordx4 v[236:237], v[244:247], off offset:256
	s_cbranch_vccnz .LBB0_1109
	v_lshlrev_b32_e32 v48, 16, v150
	v_and_b32_e32 v49, 0xffff0000, v150
	v_pk_add_f32 v[44:45], v[44:45], v[48:49]
	v_lshlrev_b32_e32 v48, 16, v151
	v_and_b32_e32 v49, 0xffff0000, v151
	v_pk_add_f32 v[46:47], v[46:47], v[48:49]

; DEVI unsigned pk_bf16(float lo, float hi) { const f32x2_t v = {lo, hi}; const bf16x2_t b = __builtin_convertvector(v, bf16x2_t); return __builtin_bit_cast(unsigned, b); }
; DEVI float bf_lo(unsigned u) { return __uint_as_float(u << 16); }
; DEVI float bf_hi(unsigned u) { return __uint_as_float(u & 0xffff0000u); }
;     DEVI void operator()(const f32x4 (&acc)[2][2][4][2], const pg8::Unit& u, int wr, int wc, int l15, int g) const {
;     ...
;                     unsigned pk[2][2];
; #pragma unroll
;                     for (int n = 0; n < 2; ++n) {
;                         const f32x4 a = acc[ai][bj][m][n];
;                         const u32x2 gg = gq[m][bj][n];
;                         f32x4 t;
;                         t[0] = a[0] * bf_lo(gg.x); t[1] = a[1] * bf_hi(gg.x); t[2] = a[2] * bf_lo(gg.y); t[3] = a[3] * bf_hi(gg.y);
;                         if (u.w) { const u32x2 q = pv[m][bj][n]; t[0] += bf_lo(q.x); t[1] += bf_hi(q.x); t[2] += bf_lo(q.y); t[3] += bf_hi(q.y); }
;                         pk[n][0] = pk_bf16(t[0], t[1]); pk[n][1] = pk_bf16(t[2], t[3]);
;                     }
;                     const auto r0 = __builtin_amdgcn_permlane16_swap(pk[0][0], pk[1][0], false, false);
;                     const auto r1 = __builtin_amdgcn_permlane16_swap(pk[0][1], pk[1][1], false, false);
;                     const u32x4 o = (u32x4){r0[0], r1[0], r0[1], r1[1]};
;                     *(u32x4*)(MX + (size_t)tok * 1024 + u.pn * 256 + 32 * wc + 128 * bj + 16 * (g & 1) + 8 * (g >> 1)) = o;
.LBB0_1111:
	v_cvt_pk_bf16_f32 v44, v44, v45
	v_cvt_pk_bf16_f32 v45, v46, v47
	v_add_u32_e32 v46, 0x90, v140
	v_ashrrev_i32_e32 v47, 31, v46
	v_lshlrev_b64 v[46:47], 11, v[46:47]
	v_lshl_add_u64 v[48:49], s[12:13], 0, v[46:47]
	v_cvt_pk_bf16_f32 v46, v40, v41
	v_cvt_pk_bf16_f32 v47, v42, v43
	v_lshl_add_u64 v[40:41], s[24:25], 1, v[48:49]
	s_waitcnt vmcnt(3)
	v_lshlrev_b32_e32 v42, 16, v68
	v_and_b32_e32 v43, 0xffff0000, v68
	v_lshl_add_u64 v[40:41], v[40:41], 0, v[132:133]
	v_mov_b32_e32 v139, v133
	v_pk_mul_f32 v[36:37], v[36:37], v[42:43]
	v_lshlrev_b32_e32 v42, 16, v69
	v_and_b32_e32 v43, 0xffff0000, v69
	v_permlane16_swap_b32_e32 v44, v46
	v_permlane16_swap_b32_e32 v45, v47
	v_lshl_add_u64 v[40:41], v[40:41], 0, v[138:139]
	s_and_b64 vcc, exec, s[4:5]
	v_pk_mul_f32 v[38:39], v[38:39], v[42:43]
	ds_bpermute_b32 v236, v239, v40
	ds_bpermute_b32 v237, v239, v41
	ds_bpermute_b32 v240, v239, v44
	ds_bpermute_b32 v241, v239, v45
	ds_bpermute_b32 v242, v239, v46
	ds_bpermute_b32 v243, v239, v47
	s_waitcnt lgkmcnt(0)
	global_store_dwordx4 v[236:237], v[240:243], off
	s_cbranch_vccnz .LBB0_1113
	v_lshlrev_b32_e32 v42, 16, v146
	v_and_b32_e32 v43, 0xffff0000, v146
	v_pk_add_f32 v[36:37], v[36:37], v[42:43]
	v_lshlrev_b32_e32 v42, 16, v147
	v_and_b32_e32 v43, 0xffff0000, v147
	v_pk_add_f32 v[38:39], v[38:39], v[42:43]

; DEVI unsigned pk_bf16(float lo, float hi) { const f32x2_t v = {lo, hi}; const bf16x2_t b = __builtin_convertvector(v, bf16x2_t); return __builtin_bit_cast(unsigned, b); }
; DEVI float bf_lo(unsigned u) { return __uint_as_float(u << 16); }
; DEVI float bf_hi(unsigned u) { return __uint_as_float(u & 0xffff0000u); }
;     DEVI void operator()(const f32x4 (&acc)[2][2][4][2], const pg8::Unit& u, int wr, int wc, int l15, int g) const {
;     ...
;             for (int m = 2 * mh; m < 2 * mh + 2; ++m) {
;                 const int tok = u.pm * 256 + 128 * ai + 64 * wr + 16 * m + l15;
; #pragma unroll
;                 for (int bj = 0; bj < 2; ++bj)
; #pragma unroll
;                     for (int n = 0; n < 2; ++n) {
;                         const int col = colb + 128 * bj + 16 * n;
;                         gq[m][bj][n] = *(const u32x2*)(G + (size_t)tok * 2048 + (u.w ? 1024 : 0) + col);
;                         if (u.w) pv[m][bj][n] = *(const u32x2*)(MX + (size_t)tok * 1024 + col);
;                     }
;     ...
;                     unsigned pk[2][2];
; #pragma unroll
;                     for (int n = 0; n < 2; ++n) {
;                         const f32x4 a = acc[ai][bj][m][n];
;                         const u32x2 gg = gq[m][bj][n];
;                         f32x4 t;
;                         t[0] = a[0] * bf_lo(gg.x); t[1] = a[1] * bf_hi(gg.x); t[2] = a[2] * bf_lo(gg.y); t[3] = a[3] * bf_hi(gg.y);
;                         if (u.w) { const u32x2 q = pv[m][bj][n]; t[0] += bf_lo(q.x); t[1] += bf_hi(q.x); t[2] += bf_lo(q.y); t[3] += bf_hi(q.y); }
;                         pk[n][0] = pk_bf16(t[0], t[1]); pk[n][1] = pk_bf16(t[2], t[3]);
;                     }
;                     const auto r0 = __builtin_amdgcn_permlane16_swap(pk[0][0], pk[1][0], false, false);
;                     const auto r1 = __builtin_amdgcn_permlane16_swap(pk[0][1], pk[1][1], false, false);
;                     const u32x4 o = (u32x4){r0[0], r1[0], r0[1], r1[1]};
;                     *(u32x4*)(MX + (size_t)tok * 1024 + u.pn * 256 + 32 * wc + 128 * bj + 16 * (g & 1) + 8 * (g >> 1)) = o;
.LBB0_1115:
	v_cvt_pk_bf16_f32 v36, v36, v37
	v_cvt_pk_bf16_f32 v37, v38, v39
	v_cvt_pk_bf16_f32 v38, v32, v33
	v_or_b32_e32 v32, 32, v64
	v_ashrrev_i32_e32 v33, 31, v32
	v_cvt_pk_bf16_f32 v39, v34, v35
	v_lshlrev_b64 v[34:35], 12, v[32:33]
	v_permlane16_swap_b32_e32 v36, v38
	v_permlane16_swap_b32_e32 v37, v39
	v_lshl_add_u64 v[34:35], s[26:27], 0, v[34:35]
	ds_bpermute_b32 v236, v239, v40
	ds_bpermute_b32 v237, v239, v41
	ds_bpermute_b32 v244, v239, v36
	ds_bpermute_b32 v245, v239, v37
	ds_bpermute_b32 v246, v239, v38
	ds_bpermute_b32 v247, v239, v39
	s_waitcnt lgkmcnt(0)
	global_store_dwordx4 v[236:237], v[244:247], off offset:256
	v_lshl_add_u64 v[34:35], v[142:143], 1, v[34:35]
	global_load_dwordx2 v[46:47], v[34:35], off
	v_lshlrev_b64 v[32:33], 11, v[32:33]
	v_lshl_add_u64 v[32:33], s[88:89], 0, v[32:33]
	s_and_b64 vcc, exec, s[4:5]
	v_lshl_add_u64 v[32:33], v[142:143], 1, v[32:33]
	s_cbranch_vccnz .LBB0_1119
	global_load_dwordx2 v[110:111], v[32:33], off
	global_load_dwordx2 v[44:45], v[34:35], off offset:32
	s_and_b64 vcc, exec, s[4:5]
	s_cbranch_vccz .LBB0_1120

; DEVI unsigned pk_bf16(float lo, float hi) { const f32x2_t v = {lo, hi}; const bf16x2_t b = __builtin_convertvector(v, bf16x2_t); return __builtin_bit_cast(unsigned, b); }
; DEVI float bf_lo(unsigned u) { return __uint_as_float(u << 16); }
; DEVI float bf_hi(unsigned u) { return __uint_as_float(u & 0xffff0000u); }
;     DEVI void operator()(const f32x4 (&acc)[2][2][4][2], const pg8::Unit& u, int wr, int wc, int l15, int g) const {
;     ...
;                     unsigned pk[2][2];
; #pragma unroll
;                     for (int n = 0; n < 2; ++n) {
;                         const f32x4 a = acc[ai][bj][m][n];
;                         const u32x2 gg = gq[m][bj][n];
;                         f32x4 t;
;                         t[0] = a[0] * bf_lo(gg.x); t[1] = a[1] * bf_hi(gg.x); t[2] = a[2] * bf_lo(gg.y); t[3] = a[3] * bf_hi(gg.y);
;                         if (u.w) { const u32x2 q = pv[m][bj][n]; t[0] += bf_lo(q.x); t[1] += bf_hi(q.x); t[2] += bf_lo(q.y); t[3] += bf_hi(q.y); }
;                         pk[n][0] = pk_bf16(t[0], t[1]); pk[n][1] = pk_bf16(t[2], t[3]);
;                     }
;                     const auto r0 = __builtin_amdgcn_permlane16_swap(pk[0][0], pk[1][0], false, false);
;                     const auto r1 = __builtin_amdgcn_permlane16_swap(pk[0][1], pk[1][1], false, false);
;                     const u32x4 o = (u32x4){r0[0], r1[0], r0[1], r1[1]};
;                     *(u32x4*)(MX + (size_t)tok * 1024 + u.pn * 256 + 32 * wc + 128 * bj + 16 * (g & 1) + 8 * (g >> 1)) = o;
.LBB0_1135:
	v_cvt_pk_bf16_f32 v28, v28, v29
	v_cvt_pk_bf16_f32 v29, v30, v31
	v_add_u32_e32 v30, 0xa0, v140
	v_ashrrev_i32_e32 v31, 31, v30
	v_lshlrev_b64 v[30:31], 11, v[30:31]
	v_lshl_add_u64 v[44:45], s[12:13], 0, v[30:31]
	v_cvt_pk_bf16_f32 v30, v24, v25
	v_cvt_pk_bf16_f32 v31, v26, v27
	v_lshl_add_u64 v[24:25], s[24:25], 1, v[44:45]
	s_waitcnt vmcnt(5)
	v_lshlrev_b32_e32 v26, 16, v42
	v_and_b32_e32 v27, 0xffff0000, v42
	v_lshl_add_u64 v[24:25], v[24:25], 0, v[132:133]
	v_mov_b32_e32 v139, v133
	v_pk_mul_f32 v[20:21], v[20:21], v[26:27]
	v_lshlrev_b32_e32 v26, 16, v43
	v_and_b32_e32 v27, 0xffff0000, v43
	v_permlane16_swap_b32_e32 v28, v30
	v_permlane16_swap_b32_e32 v29, v31
	v_lshl_add_u64 v[24:25], v[24:25], 0, v[138:139]
	s_and_b64 vcc, exec, s[4:5]
	v_pk_mul_f32 v[22:23], v[22:23], v[26:27]
	ds_bpermute_b32 v236, v239, v24
	ds_bpermute_b32 v237, v239, v25
	ds_bpermute_b32 v240, v239, v28
	ds_bpermute_b32 v241, v239, v29
	ds_bpermute_b32 v242, v239, v30
	ds_bpermute_b32 v243, v239, v31
	s_waitcnt lgkmcnt(0)
	global_store_dwordx4 v[236:237], v[240:243], off
	s_cbranch_vccnz .LBB0_1137
	v_lshlrev_b32_e32 v26, 16, v106
	v_and_b32_e32 v27, 0xffff0000, v106
	v_pk_add_f32 v[20:21], v[20:21], v[26:27]
	v_lshlrev_b32_e32 v26, 16, v107
	v_and_b32_e32 v27, 0xffff0000, v107
	v_pk_add_f32 v[22:23], v[22:23], v[26:27]

; DEVI unsigned pk_bf16(float lo, float hi) { const f32x2_t v = {lo, hi}; const bf16x2_t b = __builtin_convertvector(v, bf16x2_t); return __builtin_bit_cast(unsigned, b); }
; DEVI float bf_lo(unsigned u) { return __uint_as_float(u << 16); }
; DEVI float bf_hi(unsigned u) { return __uint_as_float(u & 0xffff0000u); }
;     DEVI void operator()(const f32x4 (&acc)[2][2][4][2], const pg8::Unit& u, int wr, int wc, int l15, int g) const {
;     ...
;                     unsigned pk[2][2];
; #pragma unroll
;                     for (int n = 0; n < 2; ++n) {
;                         const f32x4 a = acc[ai][bj][m][n];
;                         const u32x2 gg = gq[m][bj][n];
;                         f32x4 t;
;                         t[0] = a[0] * bf_lo(gg.x); t[1] = a[1] * bf_hi(gg.x); t[2] = a[2] * bf_lo(gg.y); t[3] = a[3] * bf_hi(gg.y);
;                         if (u.w) { const u32x2 q = pv[m][bj][n]; t[0] += bf_lo(q.x); t[1] += bf_hi(q.x); t[2] += bf_lo(q.y); t[3] += bf_hi(q.y); }
;                         pk[n][0] = pk_bf16(t[0], t[1]); pk[n][1] = pk_bf16(t[2], t[3]);
;                     }
;                     const auto r0 = __builtin_amdgcn_permlane16_swap(pk[0][0], pk[1][0], false, false);
;                     const auto r1 = __builtin_amdgcn_permlane16_swap(pk[0][1], pk[1][1], false, false);
;                     const u32x4 o = (u32x4){r0[0], r1[0], r0[1], r1[1]};
;                     *(u32x4*)(MX + (size_t)tok * 1024 + u.pn * 256 + 32 * wc + 128 * bj + 16 * (g & 1) + 8 * (g >> 1)) = o;
.LBB0_1139:
	v_cvt_pk_bf16_f32 v20, v20, v21
	v_cvt_pk_bf16_f32 v21, v22, v23
	v_cvt_pk_bf16_f32 v22, v16, v17
	s_waitcnt vmcnt(4)
	v_lshlrev_b32_e32 v16, 16, v38
	v_and_b32_e32 v17, 0xffff0000, v38
	v_cvt_pk_bf16_f32 v23, v18, v19
	v_pk_mul_f32 v[12:13], v[12:13], v[16:17]
	v_lshlrev_b32_e32 v16, 16, v39
	v_and_b32_e32 v17, 0xffff0000, v39
	v_permlane16_swap_b32_e32 v20, v22
	v_permlane16_swap_b32_e32 v21, v23
	s_and_b64 vcc, exec, s[4:5]
	v_pk_mul_f32 v[14:15], v[14:15], v[16:17]
	ds_bpermute_b32 v236, v239, v24
	ds_bpermute_b32 v237, v239, v25
	ds_bpermute_b32 v244, v239, v20
	ds_bpermute_b32 v245, v239, v21
	ds_bpermute_b32 v246, v239, v22
	ds_bpermute_b32 v247, v239, v23
	s_waitcnt lgkmcnt(0)
	global_store_dwordx4 v[236:237], v[244:247], off offset:256
	s_cbranch_vccnz .LBB0_1141
	v_lshlrev_b32_e32 v16, 16, v102
	v_and_b32_e32 v17, 0xffff0000, v102
	v_pk_add_f32 v[12:13], v[12:13], v[16:17]
	v_lshlrev_b32_e32 v16, 16, v103
	v_and_b32_e32 v17, 0xffff0000, v103
	v_pk_add_f32 v[14:15], v[14:15], v[16:17]

; DEVI unsigned pk_bf16(float lo, float hi) { const f32x2_t v = {lo, hi}; const bf16x2_t b = __builtin_convertvector(v, bf16x2_t); return __builtin_bit_cast(unsigned, b); }
; DEVI float bf_lo(unsigned u) { return __uint_as_float(u << 16); }
; DEVI float bf_hi(unsigned u) { return __uint_as_float(u & 0xffff0000u); }
;     DEVI void operator()(const f32x4 (&acc)[2][2][4][2], const pg8::Unit& u, int wr, int wc, int l15, int g) const {
;     ...
;                     unsigned pk[2][2];
; #pragma unroll
;                     for (int n = 0; n < 2; ++n) {
;                         const f32x4 a = acc[ai][bj][m][n];
;                         const u32x2 gg = gq[m][bj][n];
;                         f32x4 t;
;                         t[0] = a[0] * bf_lo(gg.x); t[1] = a[1] * bf_hi(gg.x); t[2] = a[2] * bf_lo(gg.y); t[3] = a[3] * bf_hi(gg.y);
;                         if (u.w) { const u32x2 q = pv[m][bj][n]; t[0] += bf_lo(q.x); t[1] += bf_hi(q.x); t[2] += bf_lo(q.y); t[3] += bf_hi(q.y); }
;                         pk[n][0] = pk_bf16(t[0], t[1]); pk[n][1] = pk_bf16(t[2], t[3]);
;                     }
;                     const auto r0 = __builtin_amdgcn_permlane16_swap(pk[0][0], pk[1][0], false, false);
;                     const auto r1 = __builtin_amdgcn_permlane16_swap(pk[0][1], pk[1][1], false, false);
;                     const u32x4 o = (u32x4){r0[0], r1[0], r0[1], r1[1]};
;                     *(u32x4*)(MX + (size_t)tok * 1024 + u.pn * 256 + 32 * wc + 128 * bj + 16 * (g & 1) + 8 * (g >> 1)) = o;
.LBB0_1143:
	v_cvt_pk_bf16_f32 v12, v12, v13
	v_cvt_pk_bf16_f32 v13, v14, v15
	v_add_u32_e32 v14, 0xb0, v140
	v_ashrrev_i32_e32 v15, 31, v14
	v_lshlrev_b64 v[14:15], 11, v[14:15]
	v_lshl_add_u64 v[16:17], s[12:13], 0, v[14:15]
	v_cvt_pk_bf16_f32 v14, v8, v9
	v_cvt_pk_bf16_f32 v15, v10, v11
	v_lshl_add_u64 v[8:9], s[24:25], 1, v[16:17]
	s_waitcnt vmcnt(3)
	v_lshlrev_b32_e32 v10, 16, v34
	v_and_b32_e32 v11, 0xffff0000, v34
	v_lshl_add_u64 v[8:9], v[8:9], 0, v[132:133]
	v_mov_b32_e32 v139, v133
	v_pk_mul_f32 v[4:5], v[4:5], v[10:11]
	v_lshlrev_b32_e32 v10, 16, v35
	v_and_b32_e32 v11, 0xffff0000, v35
	v_permlane16_swap_b32_e32 v12, v14
	v_permlane16_swap_b32_e32 v13, v15
	v_lshl_add_u64 v[8:9], v[8:9], 0, v[138:139]
	s_and_b64 vcc, exec, s[4:5]
	v_pk_mul_f32 v[6:7], v[6:7], v[10:11]
	ds_bpermute_b32 v236, v239, v8
	ds_bpermute_b32 v237, v239, v9
	ds_bpermute_b32 v240, v239, v12
	ds_bpermute_b32 v241, v239, v13
	ds_bpermute_b32 v242, v239, v14
	ds_bpermute_b32 v243, v239, v15
	s_waitcnt lgkmcnt(0)
	global_store_dwordx4 v[236:237], v[240:243], off
	s_cbranch_vccnz .LBB0_1145
	v_lshlrev_b32_e32 v10, 16, v98
	v_and_b32_e32 v11, 0xffff0000, v98
	v_pk_add_f32 v[4:5], v[4:5], v[10:11]
	v_lshlrev_b32_e32 v10, 16, v99
	v_and_b32_e32 v11, 0xffff0000, v99
	v_pk_add_f32 v[6:7], v[6:7], v[10:11]

; DEVI unsigned pk_bf16(float lo, float hi) { const f32x2_t v = {lo, hi}; const bf16x2_t b = __builtin_convertvector(v, bf16x2_t); return __builtin_bit_cast(unsigned, b); }
; DEVI float bf_lo(unsigned u) { return __uint_as_float(u << 16); }
; DEVI float bf_hi(unsigned u) { return __uint_as_float(u & 0xffff0000u); }
;     DEVI void operator()(const f32x4 (&acc)[2][2][4][2], const pg8::Unit& u, int wr, int wc, int l15, int g) const {
;     ...
;                     unsigned pk[2][2];
; #pragma unroll
;                     for (int n = 0; n < 2; ++n) {
;                         const f32x4 a = acc[ai][bj][m][n];
;                         const u32x2 gg = gq[m][bj][n];
;                         f32x4 t;
;                         t[0] = a[0] * bf_lo(gg.x); t[1] = a[1] * bf_hi(gg.x); t[2] = a[2] * bf_lo(gg.y); t[3] = a[3] * bf_hi(gg.y);
;                         if (u.w) { const u32x2 q = pv[m][bj][n]; t[0] += bf_lo(q.x); t[1] += bf_hi(q.x); t[2] += bf_lo(q.y); t[3] += bf_hi(q.y); }
;                         pk[n][0] = pk_bf16(t[0], t[1]); pk[n][1] = pk_bf16(t[2], t[3]);
;                     }
;                     const auto r0 = __builtin_amdgcn_permlane16_swap(pk[0][0], pk[1][0], false, false);
;                     const auto r1 = __builtin_amdgcn_permlane16_swap(pk[0][1], pk[1][1], false, false);
;                     const u32x4 o = (u32x4){r0[0], r1[0], r0[1], r1[1]};
;                     *(u32x4*)(MX + (size_t)tok * 1024 + u.pn * 256 + 32 * wc + 128 * bj + 16 * (g & 1) + 8 * (g >> 1)) = o;
.LBB0_1147:
	v_cvt_pk_bf16_f32 v11, v6, v7
	v_cvt_pk_bf16_f32 v10, v4, v5
	v_cvt_pk_bf16_f32 v12, v0, v1
	v_cvt_pk_bf16_f32 v13, v2, v3
	s_nop 0
	v_permlane16_swap_b32_e32 v10, v12
	v_permlane16_swap_b32_e32 v11, v13
	s_andn2_b64 vcc, exec, s[20:21]
	s_mov_b64 s[4:5], -1
	ds_bpermute_b32 v236, v239, v8
	ds_bpermute_b32 v237, v239, v9
	ds_bpermute_b32 v244, v239, v10
	ds_bpermute_b32 v245, v239, v11
	ds_bpermute_b32 v246, v239, v12
	ds_bpermute_b32 v247, v239, v13
	s_waitcnt lgkmcnt(0)
	global_store_dwordx4 v[236:237], v[244:247], off offset:256
	s_cbranch_vccnz .LBB0_1009
	s_andn2_b64 vcc, exec, s[0:1]
	s_cbranch_vccnz .LBB0_1008
	s_barrier
	s_branch .LBB0_1008

;     DEVI void operator()(const f32x4 (&acc)[2][2][4][2], const pg8::Unit& u, int wr, int wc, int l15, int g) const {
;     ...
; #pragma unroll
;             for (int m = 2 * mh; m < 2 * mh + 2; ++m) {
;                 const int tok = u.pm * 256 + 128 * ai + 64 * wr + 16 * m + l15;
;                 const float* xr = (tok < NTP) ? pp->x_p + (size_t)tok * 1024 : pp->x_s + (size_t)(tok - NTP) * 1024;
; #pragma unroll
;                 for (int bj = 0; bj < 2; ++bj)
; #pragma unroll
;                     for (int n = 0; n < 2; ++n) xv[m][bj][n] = *(const f32x4*)(xr + colb + 128 * bj + 16 * n);
;             }
; #pragma unroll
;             for (int m = 2 * mh; m < 2 * mh + 2; ++m) {
;                 const int tok = u.pm * 256 + 128 * ai + 64 * wr + 16 * m + l15;
; #pragma unroll
;                 for (int bj = 0; bj < 2; ++bj)
; #pragma unroll
;                     for (int n = 0; n < 2; ++n) *(f32x4*)(pp->out + (size_t)tok * 1024 + colb + 128 * bj + 16 * n) = xv[m][bj][n] + acc[ai][bj][m][n];
;             }
.LBB0_1231:
	v_readlane_b32 s44, v234, 2
	v_lshl_add_u32 v156, s18, 8, v164
	v_readlane_b32 s45, v234, 3
	v_readlane_b32 s47, v234, 5
	v_add_u32_e32 v128, 0xffff8000, v156
	v_ashrrev_i32_e32 v157, 31, v156
	v_cmp_gt_i32_e32 vcc, s35, v156
	v_readlane_b32 s46, v234, 4
	v_mov_b32_e32 v130, s47
	v_mov_b32_e32 v131, s45
	v_cndmask_b32_e32 v129, 0, v157, vcc
	v_cndmask_b32_e32 v128, v128, v156, vcc
	v_cndmask_b32_e32 v131, v130, v131, vcc
	v_mov_b32_e32 v130, s46
	v_mov_b32_e32 v132, s44
	v_lshl_or_b32 v154, s20, 8, v166
	v_cndmask_b32_e32 v130, v130, v132, vcc
	v_lshlrev_b64 v[128:129], 12, v[128:129]
	v_ashrrev_i32_e32 v155, 31, v154
	v_lshl_add_u64 v[128:129], v[130:131], 0, v[128:129]
	v_lshl_add_u64 v[128:129], v[154:155], 2, v[128:129]
	ds_bpermute_b32 v240, v238, v128
	ds_bpermute_b32 v241, v238, v129
	s_waitcnt lgkmcnt(0)
	global_load_dwordx4 v[140:143], v[240:241], off
	global_load_dwordx4 v[136:139], v[240:241], off offset:64
	global_load_dwordx4 v[132:135], v[240:241], off offset:512
	s_nop 0
	global_load_dwordx4 v[128:131], v[240:241], off offset:576
	ds_bpermute_b32 v112, v238, v112
	ds_bpermute_b32 v113, v238, v113
	ds_bpermute_b32 v114, v238, v114
	ds_bpermute_b32 v115, v238, v115
	ds_bpermute_b32 v116, v238, v116
	ds_bpermute_b32 v117, v238, v117
	ds_bpermute_b32 v118, v238, v118
	ds_bpermute_b32 v119, v238, v119
	s_waitcnt lgkmcnt(6)
	ds_bpermute_b32 v120, v238, v120
	ds_bpermute_b32 v121, v238, v121
	ds_bpermute_b32 v122, v238, v122
	ds_bpermute_b32 v123, v238, v123
	ds_bpermute_b32 v124, v238, v124
	ds_bpermute_b32 v125, v238, v125
	ds_bpermute_b32 v126, v238, v126
	ds_bpermute_b32 v127, v238, v127
	v_or_b32_e32 v160, 16, v156
	v_cmp_lt_i32_e32 vcc, s40, v160
	v_readlane_b32 s48, v234, 6
	v_readlane_b32 s49, v234, 7
	v_readlane_b32 s50, v234, 8
	v_readlane_b32 s51, v234, 9
	v_readlane_b32 s52, v234, 10
	v_readlane_b32 s53, v234, 11
	v_readlane_b32 s54, v234, 12
	v_readlane_b32 s55, v234, 13
	v_readlane_b32 s56, v234, 14
	v_readlane_b32 s57, v234, 15
	v_readlane_b32 s58, v234, 16
	v_readlane_b32 s59, v234, 17
	s_and_saveexec_b64 s[18:19], vcc
	s_xor_b64 s[18:19], exec, s[18:19]
	s_cbranch_execz .LBB0_1233
	v_add_u32_e32 v148, 0xffff8010, v156
	v_readlane_b32 s44, v234, 2
	v_lshlrev_b64 v[158:159], 12, v[148:149]
	v_readlane_b32 s46, v234, 4
	v_readlane_b32 s47, v234, 5
	v_mov_b32_e32 v161, v149
	v_readlane_b32 s45, v234, 3
	v_lshl_add_u64 v[162:163], s[46:47], 0, v[158:159]
	v_lshlrev_b64 v[158:159], 12, v[160:161]
	v_readlane_b32 s48, v234, 6
	v_readlane_b32 s49, v234, 7
	v_readlane_b32 s50, v234, 8
	v_readlane_b32 s51, v234, 9
	v_readlane_b32 s52, v234, 10
	v_readlane_b32 s53, v234, 11
	v_readlane_b32 s54, v234, 12
	v_readlane_b32 s55, v234, 13
	v_readlane_b32 s56, v234, 14
	v_readlane_b32 s57, v234, 15
	v_readlane_b32 s58, v234, 16
	v_readlane_b32 s59, v234, 17

;     DEVI void operator()(const f32x4 (&acc)[2][2][4][2], const pg8::Unit& u, int wr, int wc, int l15, int g) const {
;     ...
; #pragma unroll
;             for (int m = 2 * mh; m < 2 * mh + 2; ++m) {
;                 const int tok = u.pm * 256 + 128 * ai + 64 * wr + 16 * m + l15;
;                 const float* xr = (tok < NTP) ? pp->x_p + (size_t)tok * 1024 : pp->x_s + (size_t)(tok - NTP) * 1024;
; #pragma unroll
;                 for (int bj = 0; bj < 2; ++bj)
; #pragma unroll
;                     for (int n = 0; n < 2; ++n) xv[m][bj][n] = *(const f32x4*)(xr + colb + 128 * bj + 16 * n);
;             }
; #pragma unroll
;             for (int m = 2 * mh; m < 2 * mh + 2; ++m) {
;                 const int tok = u.pm * 256 + 128 * ai + 64 * wr + 16 * m + l15;
; #pragma unroll
;                 for (int bj = 0; bj < 2; ++bj)
; #pragma unroll
;                     for (int n = 0; n < 2; ++n) *(f32x4*)(pp->out + (size_t)tok * 1024 + colb + 128 * bj + 16 * n) = xv[m][bj][n] + acc[ai][bj][m][n];
;             }
.LBB0_1235:
	s_or_b64 exec, exec, s[18:19]
	v_lshlrev_b64 v[154:155], 2, v[154:155]
	v_lshl_add_u64 v[178:179], v[162:163], 0, v[154:155]
	ds_bpermute_b32 v242, v238, v178
	ds_bpermute_b32 v243, v238, v179
	s_waitcnt lgkmcnt(0)
	global_load_dwordx4 v[160:163], v[242:243], off
	global_load_dwordx4 v[170:173], v[242:243], off offset:64
	global_load_dwordx4 v[174:177], v[242:243], off offset:512
	s_nop 0
	global_load_dwordx4 v[178:181], v[242:243], off offset:576
	ds_bpermute_b32 v96, v238, v96
	ds_bpermute_b32 v97, v238, v97
	ds_bpermute_b32 v98, v238, v98
	ds_bpermute_b32 v99, v238, v99
	ds_bpermute_b32 v100, v238, v100
	ds_bpermute_b32 v101, v238, v101
	ds_bpermute_b32 v102, v238, v102
	ds_bpermute_b32 v103, v238, v103
	s_waitcnt lgkmcnt(6)
	ds_bpermute_b32 v104, v238, v104
	ds_bpermute_b32 v105, v238, v105
	ds_bpermute_b32 v106, v238, v106
	ds_bpermute_b32 v107, v238, v107
	ds_bpermute_b32 v108, v238, v108
	ds_bpermute_b32 v109, v238, v109
	ds_bpermute_b32 v110, v238, v110
	ds_bpermute_b32 v111, v238, v111
	v_readlane_b32 s44, v234, 24
	v_readlane_b32 s45, v234, 25
	v_readlane_b32 s46, v234, 26
	v_readlane_b32 s47, v234, 27
	v_readlane_b32 s48, v234, 28
	v_readlane_b32 s49, v234, 29
	v_readlane_b32 s50, v234, 30
	v_readlane_b32 s51, v234, 31
	v_readlane_b32 s52, v234, 32
	v_readlane_b32 s53, v234, 33
	v_readlane_b32 s54, v234, 34
	v_readlane_b32 s55, v234, 35
	v_readlane_b32 s56, v234, 36
	v_readlane_b32 s57, v234, 37
	v_readlane_b32 s58, v234, 38
	v_readlane_b32 s59, v234, 39
	v_lshlrev_b64 v[182:183], 12, v[156:157]
	s_waitcnt vmcnt(0)
	s_waitcnt lgkmcnt(0)
	v_pk_add_f32 v[128:129], v[112:113], v[128:129]
	s_mov_b64 s[18:19], s[58:59]
	v_or_b32_e32 v112, 32, v156
	v_readlane_b32 s44, v234, 2
	v_pk_add_f32 v[118:119], v[118:119], v[134:135]
	v_pk_add_f32 v[116:117], v[116:117], v[132:133]
	v_add_u32_e32 v134, 0xffff8020, v156
	v_readlane_b32 s45, v234, 3
	v_readlane_b32 s46, v234, 4
	v_readlane_b32 s47, v234, 5
	v_lshl_add_u64 v[132:133], s[18:19], 0, v[182:183]
	v_ashrrev_i32_e32 v113, 31, v112
	v_cmp_gt_i32_e32 vcc, s35, v112
	v_pk_add_f32 v[126:127], v[126:127], v[142:143]
	v_pk_add_f32 v[124:125], v[124:125], v[140:141]
	v_pk_add_f32 v[122:123], v[122:123], v[138:139]
	v_pk_add_f32 v[120:121], v[120:121], v[136:137]
	v_mov_b32_e32 v136, s47
	v_mov_b32_e32 v137, s45
	v_mov_b32_e32 v138, s46
	v_mov_b32_e32 v139, s44
	v_lshl_add_u64 v[132:133], v[132:133], 0, v[154:155]
	v_cndmask_b32_e32 v135, 0, v113, vcc
	v_cndmask_b32_e32 v134, v134, v112, vcc
	v_pk_add_f32 v[130:131], v[114:115], v[130:131]
	v_lshl_add_u64 v[114:115], s[18:19], 0, v[158:159]
	v_cndmask_b32_e32 v137, v136, v137, vcc
	v_cndmask_b32_e32 v136, v138, v139, vcc
	ds_bpermute_b32 v236, v238, v132
	ds_bpermute_b32 v237, v238, v133
	s_waitcnt lgkmcnt(0)
	global_store_dwordx4 v[236:237], v[124:127], off
	global_store_dwordx4 v[236:237], v[120:123], off offset:64
	global_store_dwordx4 v[236:237], v[116:119], off offset:512
	global_store_dwordx4 v[236:237], v[128:131], off offset:576
	v_lshl_add_u64 v[114:115], v[114:115], 0, v[154:155]
	v_lshlrev_b64 v[116:117], 12, v[134:135]
	v_lshl_add_u64 v[116:117], v[136:137], 0, v[116:117]
	v_lshl_add_u64 v[116:117], v[116:117], 0, v[154:155]
	v_readlane_b32 s48, v234, 6
	v_readlane_b32 s49, v234, 7
	v_readlane_b32 s50, v234, 8
	v_readlane_b32 s51, v234, 9
	v_readlane_b32 s52, v234, 10
	v_readlane_b32 s53, v234, 11
	v_readlane_b32 s54, v234, 12
	v_readlane_b32 s55, v234, 13
	v_readlane_b32 s56, v234, 14
	v_readlane_b32 s57, v234, 15
	v_readlane_b32 s58, v234, 16
	v_readlane_b32 s59, v234, 17
	s_waitcnt lgkmcnt(0)
	v_pk_add_f32 v[110:111], v[110:111], v[162:163]
	v_pk_add_f32 v[108:109], v[108:109], v[160:161]
	v_pk_add_f32 v[106:107], v[106:107], v[172:173]
	v_pk_add_f32 v[104:105], v[104:105], v[170:171]
	v_pk_add_f32 v[102:103], v[102:103], v[176:177]
	v_pk_add_f32 v[100:101], v[100:101], v[174:175]
	v_pk_add_f32 v[98:99], v[98:99], v[180:181]
	v_pk_add_f32 v[96:97], v[96:97], v[178:179]
	ds_bpermute_b32 v236, v238, v114
	ds_bpermute_b32 v237, v238, v115
	s_waitcnt lgkmcnt(0)
	global_store_dwordx4 v[236:237], v[108:111], off
	global_store_dwordx4 v[236:237], v[104:107], off offset:64
	global_store_dwordx4 v[236:237], v[100:103], off offset:512
	global_store_dwordx4 v[236:237], v[96:99], off offset:576
	ds_bpermute_b32 v240, v238, v116
	ds_bpermute_b32 v241, v238, v117
	s_waitcnt lgkmcnt(0)
	global_load_dwordx4 v[108:111], v[240:241], off
	s_nop 0
	global_load_dwordx4 v[104:107], v[240:241], off offset:64
	global_load_dwordx4 v[100:103], v[240:241], off offset:512
	global_load_dwordx4 v[96:99], v[240:241], off offset:576
	ds_bpermute_b32 v80, v238, v80
	ds_bpermute_b32 v81, v238, v81
	ds_bpermute_b32 v82, v238, v82
	ds_bpermute_b32 v83, v238, v83
	ds_bpermute_b32 v84, v238, v84
	ds_bpermute_b32 v85, v238, v85
	ds_bpermute_b32 v86, v238, v86
	ds_bpermute_b32 v87, v238, v87
	s_waitcnt lgkmcnt(6)
	ds_bpermute_b32 v88, v238, v88
	ds_bpermute_b32 v89, v238, v89
	ds_bpermute_b32 v90, v238, v90
	ds_bpermute_b32 v91, v238, v91
	ds_bpermute_b32 v92, v238, v92
	ds_bpermute_b32 v93, v238, v93
	ds_bpermute_b32 v94, v238, v94
	ds_bpermute_b32 v95, v238, v95
	v_or_b32_e32 v116, 48, v156
	v_cmp_lt_i32_e32 vcc, s40, v116
	s_and_saveexec_b64 s[18:19], vcc
	s_xor_b64 s[18:19], exec, s[18:19]
	s_cbranch_execz .LBB0_1237
	v_add_u32_e32 v148, 0xffff8030, v156
	v_readlane_b32 s44, v234, 2
	v_lshlrev_b64 v[114:115], 12, v[148:149]
	v_readlane_b32 s46, v234, 4
	v_readlane_b32 s47, v234, 5
	v_mov_b32_e32 v117, v149
	v_readlane_b32 s45, v234, 3
	v_lshl_add_u64 v[118:119], s[46:47], 0, v[114:115]
	v_lshlrev_b64 v[114:115], 12, v[116:117]
	v_readlane_b32 s48, v234, 6
	v_readlane_b32 s49, v234, 7
	v_readlane_b32 s50, v234, 8
	v_readlane_b32 s51, v234, 9
	v_readlane_b32 s52, v234, 10
	v_readlane_b32 s53, v234, 11
	v_readlane_b32 s54, v234, 12
	v_readlane_b32 s55, v234, 13
	v_readlane_b32 s56, v234, 14
	v_readlane_b32 s57, v234, 15
	v_readlane_b32 s58, v234, 16
	v_readlane_b32 s59, v234, 17

;     DEVI void operator()(const f32x4 (&acc)[2][2][4][2], const pg8::Unit& u, int wr, int wc, int l15, int g) const {
;     ...
;                 const float* xr = (tok < NTP) ? pp->x_p + (size_t)tok * 1024 : pp->x_s + (size_t)(tok - NTP) * 1024;
; #pragma unroll
;                 for (int bj = 0; bj < 2; ++bj)
; #pragma unroll
;                     for (int n = 0; n < 2; ++n) xv[m][bj][n] = *(const f32x4*)(xr + colb + 128 * bj + 16 * n);
;             }
; #pragma unroll
;             for (int m = 2 * mh; m < 2 * mh + 2; ++m) {
;                 const int tok = u.pm * 256 + 128 * ai + 64 * wr + 16 * m + l15;
; #pragma unroll
;                 for (int bj = 0; bj < 2; ++bj)
; #pragma unroll
;                     for (int n = 0; n < 2; ++n) *(f32x4*)(pp->out + (size_t)tok * 1024 + colb + 128 * bj + 16 * n) = xv[m][bj][n] + acc[ai][bj][m][n];
.LBB0_1239:
	s_or_b64 exec, exec, s[18:19]
	v_lshl_add_u64 v[128:129], v[118:119], 0, v[154:155]
	ds_bpermute_b32 v242, v238, v128
	ds_bpermute_b32 v243, v238, v129
	s_waitcnt lgkmcnt(0)
	global_load_dwordx4 v[116:119], v[242:243], off
	global_load_dwordx4 v[120:123], v[242:243], off offset:64
	global_load_dwordx4 v[124:127], v[242:243], off offset:512
	s_nop 0
	global_load_dwordx4 v[128:131], v[242:243], off offset:576
	ds_bpermute_b32 v64, v238, v64
	ds_bpermute_b32 v65, v238, v65
	ds_bpermute_b32 v66, v238, v66
	ds_bpermute_b32 v67, v238, v67
	ds_bpermute_b32 v68, v238, v68
	ds_bpermute_b32 v69, v238, v69
	ds_bpermute_b32 v70, v238, v70
	ds_bpermute_b32 v71, v238, v71
	s_waitcnt lgkmcnt(6)
	ds_bpermute_b32 v72, v238, v72
	ds_bpermute_b32 v73, v238, v73
	ds_bpermute_b32 v74, v238, v74
	ds_bpermute_b32 v75, v238, v75
	ds_bpermute_b32 v76, v238, v76
	ds_bpermute_b32 v77, v238, v77
	ds_bpermute_b32 v78, v238, v78
	ds_bpermute_b32 v79, v238, v79
	v_readlane_b32 s44, v234, 24
	v_readlane_b32 s45, v234, 25
	v_readlane_b32 s46, v234, 26
	v_readlane_b32 s47, v234, 27
	v_readlane_b32 s48, v234, 28
	v_readlane_b32 s49, v234, 29
	v_readlane_b32 s50, v234, 30
	v_readlane_b32 s51, v234, 31
	v_readlane_b32 s52, v234, 32
	v_readlane_b32 s53, v234, 33
	v_readlane_b32 s54, v234, 34
	v_readlane_b32 s55, v234, 35
	v_readlane_b32 s56, v234, 36
	v_readlane_b32 s57, v234, 37
	v_readlane_b32 s58, v234, 38
	v_readlane_b32 s59, v234, 39
	v_lshlrev_b64 v[112:113], 12, v[112:113]
	s_waitcnt vmcnt(4)
	s_waitcnt lgkmcnt(0)
	v_pk_add_f32 v[96:97], v[80:81], v[96:97]
	s_mov_b64 s[18:19], s[58:59]
	v_add_u32_e32 v80, 0x80, v156
	v_readlane_b32 s44, v234, 2
	v_pk_add_f32 v[86:87], v[86:87], v[102:103]
	v_pk_add_f32 v[84:85], v[84:85], v[100:101]
	v_add_u32_e32 v102, 0xffff8080, v156
	v_readlane_b32 s45, v234, 3
	v_readlane_b32 s46, v234, 4
	v_readlane_b32 s47, v234, 5
	v_lshl_add_u64 v[100:101], s[18:19], 0, v[112:113]
	v_ashrrev_i32_e32 v81, 31, v80
	v_cmp_gt_i32_e32 vcc, s35, v80
	v_pk_add_f32 v[94:95], v[94:95], v[110:111]
	v_pk_add_f32 v[92:93], v[92:93], v[108:109]
	v_pk_add_f32 v[90:91], v[90:91], v[106:107]
	v_pk_add_f32 v[88:89], v[88:89], v[104:105]
	v_mov_b32_e32 v104, s47
	v_mov_b32_e32 v105, s45
	v_mov_b32_e32 v106, s46
	v_mov_b32_e32 v107, s44
	v_lshl_add_u64 v[100:101], v[100:101], 0, v[154:155]
	v_cndmask_b32_e32 v103, 0, v81, vcc
	v_cndmask_b32_e32 v102, v102, v80, vcc
	v_pk_add_f32 v[98:99], v[82:83], v[98:99]
	v_lshl_add_u64 v[82:83], s[18:19], 0, v[114:115]
	v_cndmask_b32_e32 v105, v104, v105, vcc
	v_cndmask_b32_e32 v104, v106, v107, vcc
	ds_bpermute_b32 v236, v238, v100
	ds_bpermute_b32 v237, v238, v101
	s_waitcnt lgkmcnt(0)
	global_store_dwordx4 v[236:237], v[92:95], off
	global_store_dwordx4 v[236:237], v[88:91], off offset:64
	global_store_dwordx4 v[236:237], v[84:87], off offset:512
	global_store_dwordx4 v[236:237], v[96:99], off offset:576
	v_lshl_add_u64 v[82:83], v[82:83], 0, v[154:155]
	v_lshlrev_b64 v[84:85], 12, v[102:103]
	v_lshl_add_u64 v[84:85], v[104:105], 0, v[84:85]
	v_lshl_add_u64 v[84:85], v[84:85], 0, v[154:155]
	v_readlane_b32 s48, v234, 6
	v_readlane_b32 s49, v234, 7
	v_readlane_b32 s50, v234, 8
	v_readlane_b32 s51, v234, 9
	v_readlane_b32 s52, v234, 10
	v_readlane_b32 s53, v234, 11
	v_readlane_b32 s54, v234, 12
	v_readlane_b32 s55, v234, 13
	v_readlane_b32 s56, v234, 14
	v_readlane_b32 s57, v234, 15
	v_readlane_b32 s58, v234, 16
	v_readlane_b32 s59, v234, 17
	s_waitcnt vmcnt(7)
	s_waitcnt lgkmcnt(0)
	v_pk_add_f32 v[78:79], v[78:79], v[118:119]
	v_pk_add_f32 v[76:77], v[76:77], v[116:117]
	s_waitcnt vmcnt(6)
	v_pk_add_f32 v[74:75], v[74:75], v[122:123]
	v_pk_add_f32 v[72:73], v[72:73], v[120:121]
	s_waitcnt vmcnt(5)
	v_pk_add_f32 v[70:71], v[70:71], v[126:127]
	v_pk_add_f32 v[68:69], v[68:69], v[124:125]
	s_waitcnt vmcnt(4)
	v_pk_add_f32 v[66:67], v[66:67], v[130:131]
	v_pk_add_f32 v[64:65], v[64:65], v[128:129]
	ds_bpermute_b32 v236, v238, v82
	ds_bpermute_b32 v237, v238, v83
	s_waitcnt lgkmcnt(0)
	global_store_dwordx4 v[236:237], v[76:79], off
	global_store_dwordx4 v[236:237], v[72:75], off offset:64
	global_store_dwordx4 v[236:237], v[68:71], off offset:512
	global_store_dwordx4 v[236:237], v[64:67], off offset:576
	ds_bpermute_b32 v240, v238, v84
	ds_bpermute_b32 v241, v238, v85
	s_waitcnt lgkmcnt(0)
	global_load_dwordx4 v[76:79], v[240:241], off
	s_nop 0
	global_load_dwordx4 v[72:75], v[240:241], off offset:64
	global_load_dwordx4 v[68:71], v[240:241], off offset:512
	global_load_dwordx4 v[64:67], v[240:241], off offset:576
	ds_bpermute_b32 v48, v238, v48
	ds_bpermute_b32 v49, v238, v49
	ds_bpermute_b32 v50, v238, v50
	ds_bpermute_b32 v51, v238, v51
	ds_bpermute_b32 v52, v238, v52
	ds_bpermute_b32 v53, v238, v53
	ds_bpermute_b32 v54, v238, v54
	ds_bpermute_b32 v55, v238, v55
	s_waitcnt lgkmcnt(6)
	ds_bpermute_b32 v56, v238, v56
	ds_bpermute_b32 v57, v238, v57
	ds_bpermute_b32 v58, v238, v58
	ds_bpermute_b32 v59, v238, v59
	ds_bpermute_b32 v60, v238, v60
	ds_bpermute_b32 v61, v238, v61
	ds_bpermute_b32 v62, v238, v62
	ds_bpermute_b32 v63, v238, v63
	v_add_u32_e32 v84, 0x90, v156
	v_cmp_lt_i32_e32 vcc, s40, v84
	s_and_saveexec_b64 s[18:19], vcc
	s_xor_b64 s[18:19], exec, s[18:19]
	s_cbranch_execz .LBB0_1241
	v_add_u32_e32 v148, 0xffff8090, v156
	v_readlane_b32 s44, v234, 2
	v_lshlrev_b64 v[82:83], 12, v[148:149]
	v_readlane_b32 s46, v234, 4
	v_readlane_b32 s47, v234, 5
	v_mov_b32_e32 v85, v149
	v_readlane_b32 s45, v234, 3
	v_lshl_add_u64 v[86:87], s[46:47], 0, v[82:83]
	v_lshlrev_b64 v[82:83], 12, v[84:85]
	v_readlane_b32 s48, v234, 6
	v_readlane_b32 s49, v234, 7
	v_readlane_b32 s50, v234, 8
	v_readlane_b32 s51, v234, 9
	v_readlane_b32 s52, v234, 10
	v_readlane_b32 s53, v234, 11
	v_readlane_b32 s54, v234, 12
	v_readlane_b32 s55, v234, 13
	v_readlane_b32 s56, v234, 14
	v_readlane_b32 s57, v234, 15
	v_readlane_b32 s58, v234, 16
	v_readlane_b32 s59, v234, 17

;     DEVI void operator()(const f32x4 (&acc)[2][2][4][2], const pg8::Unit& u, int wr, int wc, int l15, int g) const {
;     ...
;                 const float* xr = (tok < NTP) ? pp->x_p + (size_t)tok * 1024 : pp->x_s + (size_t)(tok - NTP) * 1024;
; #pragma unroll
;                 for (int bj = 0; bj < 2; ++bj)
; #pragma unroll
;                     for (int n = 0; n < 2; ++n) xv[m][bj][n] = *(const f32x4*)(xr + colb + 128 * bj + 16 * n);
;             }
; #pragma unroll
;             for (int m = 2 * mh; m < 2 * mh + 2; ++m) {
;                 const int tok = u.pm * 256 + 128 * ai + 64 * wr + 16 * m + l15;
; #pragma unroll
;                 for (int bj = 0; bj < 2; ++bj)
; #pragma unroll
;                     for (int n = 0; n < 2; ++n) *(f32x4*)(pp->out + (size_t)tok * 1024 + colb + 128 * bj + 16 * n) = xv[m][bj][n] + acc[ai][bj][m][n];
.LBB0_1243:
	s_or_b64 exec, exec, s[18:19]
	v_lshl_add_u64 v[100:101], v[86:87], 0, v[154:155]
	ds_bpermute_b32 v242, v238, v100
	ds_bpermute_b32 v243, v238, v101
	s_waitcnt lgkmcnt(0)
	global_load_dwordx4 v[84:87], v[242:243], off
	global_load_dwordx4 v[88:91], v[242:243], off offset:64
	global_load_dwordx4 v[92:95], v[242:243], off offset:512
	global_load_dwordx4 v[96:99], v[242:243], off offset:576
	ds_bpermute_b32 v32, v238, v32
	ds_bpermute_b32 v33, v238, v33
	ds_bpermute_b32 v34, v238, v34
	ds_bpermute_b32 v35, v238, v35
	ds_bpermute_b32 v36, v238, v36
	ds_bpermute_b32 v37, v238, v37
	ds_bpermute_b32 v38, v238, v38
	ds_bpermute_b32 v39, v238, v39
	s_waitcnt lgkmcnt(6)
	ds_bpermute_b32 v40, v238, v40
	ds_bpermute_b32 v41, v238, v41
	ds_bpermute_b32 v42, v238, v42
	ds_bpermute_b32 v43, v238, v43
	ds_bpermute_b32 v44, v238, v44
	ds_bpermute_b32 v45, v238, v45
	ds_bpermute_b32 v46, v238, v46
	ds_bpermute_b32 v47, v238, v47
	v_readlane_b32 s44, v234, 24
	v_readlane_b32 s45, v234, 25
	v_readlane_b32 s46, v234, 26
	v_readlane_b32 s47, v234, 27
	v_readlane_b32 s48, v234, 28
	v_readlane_b32 s49, v234, 29
	v_readlane_b32 s50, v234, 30
	v_readlane_b32 s51, v234, 31
	v_readlane_b32 s52, v234, 32
	v_readlane_b32 s53, v234, 33
	v_readlane_b32 s54, v234, 34
	v_readlane_b32 s55, v234, 35
	v_readlane_b32 s56, v234, 36
	v_readlane_b32 s57, v234, 37
	v_readlane_b32 s58, v234, 38
	v_readlane_b32 s59, v234, 39
	v_lshlrev_b64 v[80:81], 12, v[80:81]
	s_waitcnt vmcnt(4)
	s_waitcnt lgkmcnt(0)
	v_pk_add_f32 v[64:65], v[48:49], v[64:65]
	s_mov_b64 s[18:19], s[58:59]
	v_add_u32_e32 v48, 0xa0, v156
	v_readlane_b32 s44, v234, 2
	v_pk_add_f32 v[54:55], v[54:55], v[70:71]
	v_pk_add_f32 v[52:53], v[52:53], v[68:69]
	v_add_u32_e32 v70, 0xffff80a0, v156
	v_readlane_b32 s45, v234, 3
	v_readlane_b32 s46, v234, 4
	v_readlane_b32 s47, v234, 5
	v_lshl_add_u64 v[68:69], s[18:19], 0, v[80:81]
	v_ashrrev_i32_e32 v49, 31, v48
	v_cmp_gt_i32_e32 vcc, s35, v48
	v_pk_add_f32 v[62:63], v[62:63], v[78:79]
	v_pk_add_f32 v[60:61], v[60:61], v[76:77]
	v_pk_add_f32 v[58:59], v[58:59], v[74:75]
	v_pk_add_f32 v[56:57], v[56:57], v[72:73]
	v_mov_b32_e32 v72, s47
	v_mov_b32_e32 v73, s45
	v_mov_b32_e32 v74, s46
	v_mov_b32_e32 v75, s44
	v_lshl_add_u64 v[68:69], v[68:69], 0, v[154:155]
	v_cndmask_b32_e32 v71, 0, v49, vcc
	v_cndmask_b32_e32 v70, v70, v48, vcc
	v_pk_add_f32 v[66:67], v[50:51], v[66:67]
	v_lshl_add_u64 v[50:51], s[18:19], 0, v[82:83]
	v_cndmask_b32_e32 v73, v72, v73, vcc
	v_cndmask_b32_e32 v72, v74, v75, vcc
	ds_bpermute_b32 v236, v238, v68
	ds_bpermute_b32 v237, v238, v69
	s_waitcnt lgkmcnt(0)
	global_store_dwordx4 v[236:237], v[60:63], off
	global_store_dwordx4 v[236:237], v[56:59], off offset:64
	global_store_dwordx4 v[236:237], v[52:55], off offset:512
	global_store_dwordx4 v[236:237], v[64:67], off offset:576
	v_lshl_add_u64 v[50:51], v[50:51], 0, v[154:155]
	v_lshlrev_b64 v[52:53], 12, v[70:71]
	v_lshl_add_u64 v[52:53], v[72:73], 0, v[52:53]
	v_lshl_add_u64 v[52:53], v[52:53], 0, v[154:155]
	v_readlane_b32 s48, v234, 6
	v_readlane_b32 s49, v234, 7
	v_readlane_b32 s50, v234, 8
	v_readlane_b32 s51, v234, 9
	v_readlane_b32 s52, v234, 10
	v_readlane_b32 s53, v234, 11
	v_readlane_b32 s54, v234, 12
	v_readlane_b32 s55, v234, 13
	v_readlane_b32 s56, v234, 14
	v_readlane_b32 s57, v234, 15
	v_readlane_b32 s58, v234, 16
	v_readlane_b32 s59, v234, 17
	s_waitcnt vmcnt(7)
	s_waitcnt lgkmcnt(0)
	v_pk_add_f32 v[46:47], v[46:47], v[86:87]
	v_pk_add_f32 v[44:45], v[44:45], v[84:85]
	s_waitcnt vmcnt(6)
	v_pk_add_f32 v[42:43], v[42:43], v[90:91]
	v_pk_add_f32 v[40:41], v[40:41], v[88:89]
	s_waitcnt vmcnt(5)
	v_pk_add_f32 v[38:39], v[38:39], v[94:95]
	v_pk_add_f32 v[36:37], v[36:37], v[92:93]
	s_waitcnt vmcnt(4)
	v_pk_add_f32 v[34:35], v[34:35], v[98:99]
	v_pk_add_f32 v[32:33], v[32:33], v[96:97]
	ds_bpermute_b32 v236, v238, v50
	ds_bpermute_b32 v237, v238, v51
	s_waitcnt lgkmcnt(0)
	global_store_dwordx4 v[236:237], v[44:47], off
	global_store_dwordx4 v[236:237], v[40:43], off offset:64
	global_store_dwordx4 v[236:237], v[36:39], off offset:512
	global_store_dwordx4 v[236:237], v[32:35], off offset:576
	ds_bpermute_b32 v240, v238, v52
	ds_bpermute_b32 v241, v238, v53
	s_waitcnt lgkmcnt(0)
	global_load_dwordx4 v[44:47], v[240:241], off
	s_nop 0
	global_load_dwordx4 v[40:43], v[240:241], off offset:64
	global_load_dwordx4 v[36:39], v[240:241], off offset:512
	global_load_dwordx4 v[32:35], v[240:241], off offset:576
	ds_bpermute_b32 v16, v238, v16
	ds_bpermute_b32 v17, v238, v17
	ds_bpermute_b32 v18, v238, v18
	ds_bpermute_b32 v19, v238, v19
	ds_bpermute_b32 v20, v238, v20
	ds_bpermute_b32 v21, v238, v21
	ds_bpermute_b32 v22, v238, v22
	ds_bpermute_b32 v23, v238, v23
	s_waitcnt lgkmcnt(6)
	ds_bpermute_b32 v24, v238, v24
	ds_bpermute_b32 v25, v238, v25
	ds_bpermute_b32 v26, v238, v26
	ds_bpermute_b32 v27, v238, v27
	ds_bpermute_b32 v28, v238, v28
	ds_bpermute_b32 v29, v238, v29
	ds_bpermute_b32 v30, v238, v30
	ds_bpermute_b32 v31, v238, v31
	v_add_u32_e32 v52, 0xb0, v156
	v_cmp_lt_i32_e32 vcc, s40, v52
	s_and_saveexec_b64 s[18:19], vcc
	s_xor_b64 s[18:19], exec, s[18:19]
	s_cbranch_execz .LBB0_1245
	v_add_u32_e32 v148, 0xffff80b0, v156
	v_readlane_b32 s44, v234, 2
	v_lshlrev_b64 v[50:51], 12, v[148:149]
	v_readlane_b32 s46, v234, 4
	v_readlane_b32 s47, v234, 5
	v_mov_b32_e32 v53, v149
	v_readlane_b32 s45, v234, 3
	v_lshl_add_u64 v[54:55], s[46:47], 0, v[50:51]
	v_lshlrev_b64 v[50:51], 12, v[52:53]
	v_readlane_b32 s48, v234, 6
	v_readlane_b32 s49, v234, 7
	v_readlane_b32 s50, v234, 8
	v_readlane_b32 s51, v234, 9
	v_readlane_b32 s52, v234, 10
	v_readlane_b32 s53, v234, 11
	v_readlane_b32 s54, v234, 12
	v_readlane_b32 s55, v234, 13
	v_readlane_b32 s56, v234, 14
	v_readlane_b32 s57, v234, 15
	v_readlane_b32 s58, v234, 16
	v_readlane_b32 s59, v234, 17

; #define PG8_BAR __builtin_amdgcn_s_barrier()
; template <class Epi, class Sched>
; __device__ __forceinline__ void gemm_phase(PG8_LAS unsigned char* lds, const Gemm g, const Sched& S, const Epi& E) {
;     ...
;         if (!has_next) break;
; #pragma unroll
;         for (int a = 0; a < 2; ++a)
; #pragma unroll
;             for (int b = 0; b < 2; ++b)
; #pragma unroll
;                 for (int m = 0; m < 4; ++m)
; #pragma unroll
;                     for (int n = 0; n < 2; ++n) acc[a][b][m][n] = (f32x4){0.f, 0.f, 0.f, 0.f};
;         cur = nxt; cA = nA; cB = nB; ++ui;
;         if (wr == 1) PG8_BAR;
;     DEVI void operator()(const f32x4 (&acc)[2][2][4][2], const pg8::Unit& u, int wr, int wc, int l15, int g) const {
;     ...
;             for (int m = 2 * mh; m < 2 * mh + 2; ++m) {
;                 const int tok = u.pm * 256 + 128 * ai + 64 * wr + 16 * m + l15;
; #pragma unroll
;                 for (int bj = 0; bj < 2; ++bj)
; #pragma unroll
;                     for (int n = 0; n < 2; ++n) *(f32x4*)(pp->out + (size_t)tok * 1024 + colb + 128 * bj + 16 * n) = xv[m][bj][n] + acc[ai][bj][m][n];
.LBB0_1247:
	s_or_b64 exec, exec, s[18:19]
	v_lshl_add_u64 v[68:69], v[54:55], 0, v[154:155]
	ds_bpermute_b32 v242, v238, v68
	ds_bpermute_b32 v243, v238, v69
	s_waitcnt lgkmcnt(0)
	global_load_dwordx4 v[52:55], v[242:243], off
	global_load_dwordx4 v[56:59], v[242:243], off offset:64
	global_load_dwordx4 v[60:63], v[242:243], off offset:512
	global_load_dwordx4 v[64:67], v[242:243], off offset:576
	ds_bpermute_b32 v0, v238, v0
	ds_bpermute_b32 v1, v238, v1
	ds_bpermute_b32 v2, v238, v2
	ds_bpermute_b32 v3, v238, v3
	ds_bpermute_b32 v4, v238, v4
	ds_bpermute_b32 v5, v238, v5
	ds_bpermute_b32 v6, v238, v6
	ds_bpermute_b32 v7, v238, v7
	s_waitcnt lgkmcnt(6)
	ds_bpermute_b32 v8, v238, v8
	ds_bpermute_b32 v9, v238, v9
	ds_bpermute_b32 v10, v238, v10
	ds_bpermute_b32 v11, v238, v11
	ds_bpermute_b32 v12, v238, v12
	ds_bpermute_b32 v13, v238, v13
	ds_bpermute_b32 v14, v238, v14
	ds_bpermute_b32 v15, v238, v15
	v_readlane_b32 s44, v234, 24
	v_readlane_b32 s58, v234, 38
	v_readlane_b32 s59, v234, 39
	v_lshlrev_b64 v[48:49], 12, v[48:49]
	s_mov_b64 s[18:19], s[58:59]
	s_waitcnt vmcnt(4)
	s_waitcnt lgkmcnt(0)
	v_pk_add_f32 v[18:19], v[18:19], v[34:35]
	v_pk_add_f32 v[16:17], v[16:17], v[32:33]
	v_lshl_add_u64 v[32:33], s[18:19], 0, v[50:51]
	v_lshl_add_u64 v[34:35], s[18:19], 0, v[48:49]
	v_pk_add_f32 v[30:31], v[30:31], v[46:47]
	v_pk_add_f32 v[28:29], v[28:29], v[44:45]
	v_lshl_add_u64 v[32:33], v[32:33], 0, v[154:155]
	v_lshl_add_u64 v[34:35], v[34:35], 0, v[154:155]
	s_andn2_b64 vcc, exec, s[16:17]
	s_mov_b64 s[16:17], -1
	v_pk_add_f32 v[26:27], v[26:27], v[42:43]
	v_pk_add_f32 v[24:25], v[24:25], v[40:41]
	v_pk_add_f32 v[22:23], v[22:23], v[38:39]
	v_pk_add_f32 v[20:21], v[20:21], v[36:37]
	v_readlane_b32 s45, v234, 25
	v_readlane_b32 s46, v234, 26
	v_readlane_b32 s47, v234, 27
	v_readlane_b32 s48, v234, 28
	v_readlane_b32 s49, v234, 29
	v_readlane_b32 s50, v234, 30
	v_readlane_b32 s51, v234, 31
	v_readlane_b32 s52, v234, 32
	v_readlane_b32 s53, v234, 33
	v_readlane_b32 s54, v234, 34
	v_readlane_b32 s55, v234, 35
	v_readlane_b32 s56, v234, 36
	v_readlane_b32 s57, v234, 37
	ds_bpermute_b32 v236, v238, v34
	ds_bpermute_b32 v237, v238, v35
	s_waitcnt lgkmcnt(0)
	global_store_dwordx4 v[236:237], v[28:31], off
	global_store_dwordx4 v[236:237], v[24:27], off offset:64
	global_store_dwordx4 v[236:237], v[20:23], off offset:512
	global_store_dwordx4 v[236:237], v[16:19], off offset:576
	s_waitcnt vmcnt(7)
	s_waitcnt lgkmcnt(0)
	v_pk_add_f32 v[14:15], v[14:15], v[54:55]
	v_pk_add_f32 v[12:13], v[12:13], v[52:53]
	s_waitcnt vmcnt(6)
	v_pk_add_f32 v[10:11], v[10:11], v[58:59]
	v_pk_add_f32 v[8:9], v[8:9], v[56:57]
	s_waitcnt vmcnt(5)
	v_pk_add_f32 v[6:7], v[6:7], v[62:63]
	v_pk_add_f32 v[4:5], v[4:5], v[60:61]
	s_waitcnt vmcnt(4)
	v_pk_add_f32 v[2:3], v[2:3], v[66:67]
	v_pk_add_f32 v[0:1], v[0:1], v[64:65]
	ds_bpermute_b32 v236, v238, v32
	ds_bpermute_b32 v237, v238, v33
	s_waitcnt lgkmcnt(0)
	global_store_dwordx4 v[236:237], v[12:15], off
	global_store_dwordx4 v[236:237], v[8:11], off offset:64
	global_store_dwordx4 v[236:237], v[4:7], off offset:512
	global_store_dwordx4 v[236:237], v[0:3], off offset:576
	s_cbranch_vccnz .LBB0_1221
	s_andn2_b64 vcc, exec, s[0:1]
	s_cbranch_vccnz .LBB0_1220
	s_barrier
	s_branch .LBB0_1220
